# all LDS-DMA loads in the six GEMM K-loops use the saddr form (SGPR base + 32-bit VGPR offset); 64-bit VALU address adds removed from load blocks
# baseline (speedup 1.0000x reference)
.LBB0_134:
	s_add_u32 s28, s66, 0xfffc0080
	s_addc_u32 s29, s67, -1
	s_add_i32 s88, 0, 0x10000
	v_add_u32_e32 v152, s88, v191
	ds_read_b128 v[128:131], v152
	ds_read_b128 v[132:135], v152 offset:1024
	ds_read_b128 v[148:151], v152 offset:2048
	ds_read_b128 v[152:155], v152 offset:3072
	s_cmp_eq_u32 vcc_lo, 12
	s_cselect_b32 s71, s5, s29
	s_cselect_b32 s70, s7, s28
	s_cselect_b32 s69, s17, s91
	s_cselect_b32 s68, s19, s85
	s_add_i32 m0, s73, 0xc000
	ds_read_b128 v[156:159], v192
	ds_read_b128 v[164:167], v192 offset:2048
	ds_read_b128 v[194:197], v192 offset:4096
	ds_read_b128 v[202:205], v192 offset:6144
	ds_read_b128 v[160:163], v192 offset:1024
	ds_read_b128 v[168:171], v192 offset:3072
	ds_read_b128 v[198:201], v192 offset:5120
	ds_read_b128 v[206:209], v192 offset:7168
	global_load_lds_dwordx4 v144, s[66:67]
	s_add_i32 m0, s73, 0xe000
	s_nop 0
	global_load_lds_dwordx4 v146, s[66:67]
	s_waitcnt lgkmcnt(8)
	s_barrier
	s_waitcnt lgkmcnt(7)
	v_mfma_f32_16x16x32_bf16 v[124:127], v[128:131], v[156:159], v[124:127]
	v_mfma_f32_16x16x32_bf16 v[120:123], v[148:151], v[156:159], v[120:123]
	s_waitcnt lgkmcnt(6)
	v_mfma_f32_16x16x32_bf16 v[108:111], v[128:131], v[164:167], v[108:111]
	v_mfma_f32_16x16x32_bf16 v[104:107], v[148:151], v[164:167], v[104:107]
	s_waitcnt lgkmcnt(5)
	v_mfma_f32_16x16x32_bf16 v[92:95], v[128:131], v[194:197], v[92:95]
	v_mfma_f32_16x16x32_bf16 v[88:91], v[148:151], v[194:197], v[88:91]
	s_waitcnt lgkmcnt(4)
	v_mfma_f32_16x16x32_bf16 v[76:79], v[128:131], v[202:205], v[76:79]
	v_mfma_f32_16x16x32_bf16 v[72:75], v[148:151], v[202:205], v[72:75]
	s_waitcnt lgkmcnt(3)
	v_mfma_f32_16x16x32_bf16 v[124:127], v[132:135], v[160:163], v[124:127]
	v_mfma_f32_16x16x32_bf16 v[120:123], v[152:155], v[160:163], v[120:123]
	s_waitcnt lgkmcnt(2)
	v_mfma_f32_16x16x32_bf16 v[108:111], v[132:135], v[168:171], v[108:111]
	v_mfma_f32_16x16x32_bf16 v[104:107], v[152:155], v[168:171], v[104:107]
	s_waitcnt lgkmcnt(1)
	v_mfma_f32_16x16x32_bf16 v[92:95], v[132:135], v[198:201], v[92:95]
	v_mfma_f32_16x16x32_bf16 v[88:91], v[152:155], v[198:201], v[88:91]
	s_waitcnt lgkmcnt(0)
	v_mfma_f32_16x16x32_bf16 v[76:79], v[132:135], v[206:209], v[76:79]
	v_mfma_f32_16x16x32_bf16 v[72:75], v[152:155], v[206:209], v[72:75]
	s_barrier
	s_add_i32 s89, 0, 0x14000
	v_add_u32_e32 v172, s89, v191
	s_add_i32 s28, s88, s72
	ds_read_b128 v[210:213], v172
	ds_read_b128 v[214:217], v172 offset:1024
	ds_read_b128 v[232:235], v172 offset:2048
	ds_read_b128 v[236:239], v172 offset:3072
	s_mov_b32 m0, s28
	s_nop 0
	global_load_lds_dwordx4 v138, s[68:69]
	s_add_i32 m0, s28, 0x2000
	s_nop 0
	global_load_lds_dwordx4 v142, s[68:69]
	s_barrier
	s_waitcnt lgkmcnt(3)
	v_mfma_f32_16x16x32_bf16 v[116:119], v[210:213], v[156:159], v[116:119]
	s_waitcnt lgkmcnt(1)
	v_mfma_f32_16x16x32_bf16 v[112:115], v[232:235], v[156:159], v[112:115]
	v_mfma_f32_16x16x32_bf16 v[100:103], v[210:213], v[164:167], v[100:103]
	v_mfma_f32_16x16x32_bf16 v[96:99], v[232:235], v[164:167], v[96:99]
	v_mfma_f32_16x16x32_bf16 v[84:87], v[210:213], v[194:197], v[84:87]
	v_mfma_f32_16x16x32_bf16 v[80:83], v[232:235], v[194:197], v[80:83]
	v_mfma_f32_16x16x32_bf16 v[68:71], v[210:213], v[202:205], v[68:71]
	v_mfma_f32_16x16x32_bf16 v[64:67], v[232:235], v[202:205], v[64:67]
	v_mfma_f32_16x16x32_bf16 v[116:119], v[214:217], v[160:163], v[116:119]
	s_waitcnt lgkmcnt(0)
	v_mfma_f32_16x16x32_bf16 v[112:115], v[236:239], v[160:163], v[112:115]
	v_mfma_f32_16x16x32_bf16 v[100:103], v[214:217], v[168:171], v[100:103]
	v_mfma_f32_16x16x32_bf16 v[96:99], v[236:239], v[168:171], v[96:99]
	v_mfma_f32_16x16x32_bf16 v[84:87], v[214:217], v[198:201], v[84:87]
	v_mfma_f32_16x16x32_bf16 v[80:83], v[236:239], v[198:201], v[80:83]
	v_mfma_f32_16x16x32_bf16 v[68:71], v[214:217], v[206:209], v[68:71]
	v_mfma_f32_16x16x32_bf16 v[64:67], v[236:239], v[206:209], v[64:67]
	s_mov_b32 m0, s73
	v_lshl_add_u64 v[240:241], s[70:71], 0, v[136:137]
	s_barrier
	ds_read_b128 v[156:159], v192 offset:16384
	ds_read_b128 v[164:167], v192 offset:18432
	ds_read_b128 v[194:197], v192 offset:20480
	ds_read_b128 v[202:205], v192 offset:22528
	ds_read_b128 v[160:163], v192 offset:17408
	ds_read_b128 v[168:171], v192 offset:19456
	ds_read_b128 v[198:201], v192 offset:21504
	ds_read_b128 v[206:209], v192 offset:23552
	global_load_lds_dwordx4 v136, s[70:71]
	v_lshl_add_u64 v[242:243], s[70:71], 0, v[140:141]
	s_mov_b32 m0, s74
	s_nop 0
	global_load_lds_dwordx4 v140, s[70:71]
	s_barrier
	s_waitcnt lgkmcnt(7)
	v_mfma_f32_16x16x32_bf16 v[60:63], v[128:131], v[156:159], v[60:63]
	v_mfma_f32_16x16x32_bf16 v[56:59], v[148:151], v[156:159], v[56:59]
	s_waitcnt lgkmcnt(6)
	v_mfma_f32_16x16x32_bf16 v[44:47], v[128:131], v[164:167], v[44:47]
	v_mfma_f32_16x16x32_bf16 v[40:43], v[148:151], v[164:167], v[40:43]
	s_waitcnt lgkmcnt(5)
	v_mfma_f32_16x16x32_bf16 v[28:31], v[128:131], v[194:197], v[28:31]
	v_mfma_f32_16x16x32_bf16 v[24:27], v[148:151], v[194:197], v[24:27]
	s_waitcnt lgkmcnt(4)
	v_mfma_f32_16x16x32_bf16 v[12:15], v[128:131], v[202:205], v[12:15]
	v_mfma_f32_16x16x32_bf16 v[8:11], v[148:151], v[202:205], v[8:11]
	s_waitcnt lgkmcnt(3)
	v_mfma_f32_16x16x32_bf16 v[60:63], v[132:135], v[160:163], v[60:63]
	v_mfma_f32_16x16x32_bf16 v[56:59], v[152:155], v[160:163], v[56:59]
	s_waitcnt lgkmcnt(2)
	v_mfma_f32_16x16x32_bf16 v[44:47], v[132:135], v[168:171], v[44:47]
	v_mfma_f32_16x16x32_bf16 v[40:43], v[152:155], v[168:171], v[40:43]
	s_waitcnt lgkmcnt(1)
	v_mfma_f32_16x16x32_bf16 v[28:31], v[132:135], v[198:201], v[28:31]
	v_mfma_f32_16x16x32_bf16 v[24:27], v[152:155], v[198:201], v[24:27]
	s_waitcnt lgkmcnt(0)
	v_mfma_f32_16x16x32_bf16 v[12:15], v[132:135], v[206:209], v[12:15]
	v_mfma_f32_16x16x32_bf16 v[8:11], v[152:155], v[206:209], v[8:11]
	s_barrier
	s_add_u32 s28, s68, 0x40000
	s_addc_u32 s29, s69, 0
	s_add_i32 s88, s89, s72
	s_mov_b32 m0, s88
	s_nop 0
	global_load_lds_dwordx4 v138, s[28:29]
	s_add_i32 m0, s88, 0x2000
	s_nop 0
	global_load_lds_dwordx4 v142, s[28:29]
	s_waitcnt vmcnt(6)
	s_barrier
	v_mfma_f32_16x16x32_bf16 v[52:55], v[210:213], v[156:159], v[52:55]
	v_mfma_f32_16x16x32_bf16 v[48:51], v[232:235], v[156:159], v[48:51]
	v_mfma_f32_16x16x32_bf16 v[36:39], v[210:213], v[164:167], v[36:39]
	v_mfma_f32_16x16x32_bf16 v[32:35], v[232:235], v[164:167], v[32:35]
	v_mfma_f32_16x16x32_bf16 v[20:23], v[210:213], v[194:197], v[20:23]
	v_mfma_f32_16x16x32_bf16 v[16:19], v[232:235], v[194:197], v[16:19]
	v_mfma_f32_16x16x32_bf16 v[4:7], v[210:213], v[202:205], v[4:7]
	v_mfma_f32_16x16x32_bf16 v[0:3], v[232:235], v[202:205], v[0:3]
	v_mfma_f32_16x16x32_bf16 v[52:55], v[214:217], v[160:163], v[52:55]
	v_mfma_f32_16x16x32_bf16 v[48:51], v[236:239], v[160:163], v[48:51]
	v_mfma_f32_16x16x32_bf16 v[36:39], v[214:217], v[168:171], v[36:39]
	v_mfma_f32_16x16x32_bf16 v[32:35], v[236:239], v[168:171], v[32:35]
	v_mfma_f32_16x16x32_bf16 v[20:23], v[214:217], v[198:201], v[20:23]
	v_mfma_f32_16x16x32_bf16 v[16:19], v[236:239], v[198:201], v[16:19]
	v_mfma_f32_16x16x32_bf16 v[4:7], v[214:217], v[206:209], v[4:7]
	v_mfma_f32_16x16x32_bf16 v[0:3], v[236:239], v[206:209], v[0:3]
	s_add_i32 s88, 0, 0x18000
	v_add_u32_e32 v152, s88, v191
	s_barrier
	ds_read_b128 v[128:131], v152
	ds_read_b128 v[132:135], v152 offset:1024
	ds_read_b128 v[148:151], v152 offset:2048
	ds_read_b128 v[152:155], v152 offset:3072
	s_add_u32 s28, s70, 0x40000
	s_addc_u32 s29, s71, 0
	s_mov_b32 m0, s75
	ds_read_b128 v[156:159], v192 offset:32768
	ds_read_b128 v[164:167], v192 offset:34816
	ds_read_b128 v[194:197], v192 offset:36864
	ds_read_b128 v[202:205], v192 offset:38912
	ds_read_b128 v[160:163], v192 offset:33792
	ds_read_b128 v[168:171], v192 offset:35840
	ds_read_b128 v[198:201], v192 offset:37888
	ds_read_b128 v[206:209], v192 offset:39936
	global_load_lds_dwordx4 v136, s[28:29]
	s_mov_b32 m0, s76
	s_nop 0
	global_load_lds_dwordx4 v140, s[28:29]
	s_waitcnt lgkmcnt(8)
	s_barrier
	s_waitcnt lgkmcnt(7)
	v_mfma_f32_16x16x32_bf16 v[124:127], v[128:131], v[156:159], v[124:127]
	v_mfma_f32_16x16x32_bf16 v[120:123], v[148:151], v[156:159], v[120:123]
	s_waitcnt lgkmcnt(6)
	v_mfma_f32_16x16x32_bf16 v[108:111], v[128:131], v[164:167], v[108:111]
	v_mfma_f32_16x16x32_bf16 v[104:107], v[148:151], v[164:167], v[104:107]
	s_waitcnt lgkmcnt(5)
	v_mfma_f32_16x16x32_bf16 v[92:95], v[128:131], v[194:197], v[92:95]
	v_mfma_f32_16x16x32_bf16 v[88:91], v[148:151], v[194:197], v[88:91]
	s_waitcnt lgkmcnt(4)
	v_mfma_f32_16x16x32_bf16 v[76:79], v[128:131], v[202:205], v[76:79]
	v_mfma_f32_16x16x32_bf16 v[72:75], v[148:151], v[202:205], v[72:75]
	s_waitcnt lgkmcnt(3)
	v_mfma_f32_16x16x32_bf16 v[124:127], v[132:135], v[160:163], v[124:127]
	v_mfma_f32_16x16x32_bf16 v[120:123], v[152:155], v[160:163], v[120:123]
	s_waitcnt lgkmcnt(2)
	v_mfma_f32_16x16x32_bf16 v[108:111], v[132:135], v[168:171], v[108:111]
	v_mfma_f32_16x16x32_bf16 v[104:107], v[152:155], v[168:171], v[104:107]
	s_waitcnt lgkmcnt(1)
	v_mfma_f32_16x16x32_bf16 v[92:95], v[132:135], v[198:201], v[92:95]
	v_mfma_f32_16x16x32_bf16 v[88:91], v[152:155], v[198:201], v[88:91]
	s_waitcnt lgkmcnt(0)
	v_mfma_f32_16x16x32_bf16 v[76:79], v[132:135], v[206:209], v[76:79]
	v_mfma_f32_16x16x32_bf16 v[72:75], v[152:155], v[206:209], v[72:75]
	s_barrier
	s_add_i32 s70, 0, 0x1c000
	s_add_i32 s28, s88, s72
	v_add_u32_e32 v174, s70, v191
	s_mov_b32 m0, s28
	ds_read_b128 v[210:213], v174
	ds_read_b128 v[214:217], v174 offset:1024
	ds_read_b128 v[232:235], v174 offset:2048
	ds_read_b128 v[236:239], v174 offset:3072
	s_add_u32 s98, s68, 0x80
	s_addc_u32 s99, s69, 0
	global_load_lds_dwordx4 v138, s[98:99]
	s_add_i32 m0, s28, 0x2000
	s_nop 0
	global_load_lds_dwordx4 v142, s[98:99]
	s_barrier
	s_waitcnt lgkmcnt(3)
	v_mfma_f32_16x16x32_bf16 v[116:119], v[210:213], v[156:159], v[116:119]
	s_waitcnt lgkmcnt(1)
	v_mfma_f32_16x16x32_bf16 v[112:115], v[232:235], v[156:159], v[112:115]
	v_mfma_f32_16x16x32_bf16 v[100:103], v[210:213], v[164:167], v[100:103]
	v_mfma_f32_16x16x32_bf16 v[96:99], v[232:235], v[164:167], v[96:99]
	v_mfma_f32_16x16x32_bf16 v[84:87], v[210:213], v[194:197], v[84:87]
	v_mfma_f32_16x16x32_bf16 v[80:83], v[232:235], v[194:197], v[80:83]
	v_mfma_f32_16x16x32_bf16 v[68:71], v[210:213], v[202:205], v[68:71]
	v_mfma_f32_16x16x32_bf16 v[64:67], v[232:235], v[202:205], v[64:67]
	v_mfma_f32_16x16x32_bf16 v[116:119], v[214:217], v[160:163], v[116:119]
	s_waitcnt lgkmcnt(0)
	v_mfma_f32_16x16x32_bf16 v[112:115], v[236:239], v[160:163], v[112:115]
	v_mfma_f32_16x16x32_bf16 v[100:103], v[214:217], v[168:171], v[100:103]
	v_mfma_f32_16x16x32_bf16 v[96:99], v[236:239], v[168:171], v[96:99]
	v_mfma_f32_16x16x32_bf16 v[84:87], v[214:217], v[198:201], v[84:87]
	v_mfma_f32_16x16x32_bf16 v[80:83], v[236:239], v[198:201], v[80:83]
	v_mfma_f32_16x16x32_bf16 v[68:71], v[214:217], v[206:209], v[68:71]
	v_mfma_f32_16x16x32_bf16 v[64:67], v[236:239], v[206:209], v[64:67]
	s_mov_b32 m0, s79
	v_lshl_add_u64 v[172:173], v[240:241], 0, s[40:41]
	s_barrier
	ds_read_b128 v[156:159], v192 offset:49152
	ds_read_b128 v[164:167], v192 offset:51200
	ds_read_b128 v[194:197], v192 offset:53248
	ds_read_b128 v[202:205], v192 offset:55296
	ds_read_b128 v[160:163], v192 offset:50176
	ds_read_b128 v[168:171], v192 offset:52224
	ds_read_b128 v[198:201], v192 offset:54272
	ds_read_b128 v[206:209], v192 offset:56320
	global_load_lds_dwordx4 v[172:173], off
	v_lshl_add_u64 v[172:173], v[242:243], 0, s[40:41]
	s_mov_b32 m0, s80
	s_nop 0
	global_load_lds_dwordx4 v[172:173], off
	s_barrier
	s_waitcnt lgkmcnt(7)
	v_mfma_f32_16x16x32_bf16 v[60:63], v[128:131], v[156:159], v[60:63]
	v_mfma_f32_16x16x32_bf16 v[56:59], v[148:151], v[156:159], v[56:59]
	s_waitcnt lgkmcnt(6)
	v_mfma_f32_16x16x32_bf16 v[44:47], v[128:131], v[164:167], v[44:47]
	v_mfma_f32_16x16x32_bf16 v[40:43], v[148:151], v[164:167], v[40:43]
	s_waitcnt lgkmcnt(5)
	v_mfma_f32_16x16x32_bf16 v[28:31], v[128:131], v[194:197], v[28:31]
	v_mfma_f32_16x16x32_bf16 v[24:27], v[148:151], v[194:197], v[24:27]
	s_waitcnt lgkmcnt(4)
	v_mfma_f32_16x16x32_bf16 v[12:15], v[128:131], v[202:205], v[12:15]
	v_mfma_f32_16x16x32_bf16 v[8:11], v[148:151], v[202:205], v[8:11]
	s_waitcnt lgkmcnt(3)
	v_mfma_f32_16x16x32_bf16 v[60:63], v[132:135], v[160:163], v[60:63]
	v_mfma_f32_16x16x32_bf16 v[56:59], v[152:155], v[160:163], v[56:59]
	s_waitcnt lgkmcnt(2)
	v_mfma_f32_16x16x32_bf16 v[44:47], v[132:135], v[168:171], v[44:47]
	v_mfma_f32_16x16x32_bf16 v[40:43], v[152:155], v[168:171], v[40:43]
	s_waitcnt lgkmcnt(1)
	v_mfma_f32_16x16x32_bf16 v[28:31], v[132:135], v[198:201], v[28:31]
	v_mfma_f32_16x16x32_bf16 v[24:27], v[152:155], v[198:201], v[24:27]
	s_waitcnt lgkmcnt(0)
	v_mfma_f32_16x16x32_bf16 v[12:15], v[132:135], v[206:209], v[12:15]
	v_mfma_f32_16x16x32_bf16 v[8:11], v[152:155], v[206:209], v[8:11]
	s_barrier
	s_add_u32 s28, s68, 0x40080
	s_addc_u32 s29, s69, 0
	s_add_i32 s68, s70, s72
	s_mov_b32 m0, s68
	s_nop 0
	global_load_lds_dwordx4 v138, s[28:29]
	s_add_i32 m0, s68, 0x2000
	s_nop 0
	global_load_lds_dwordx4 v142, s[28:29]
	s_waitcnt vmcnt(6)
	s_barrier
	v_mfma_f32_16x16x32_bf16 v[52:55], v[210:213], v[156:159], v[52:55]
	v_mfma_f32_16x16x32_bf16 v[48:51], v[232:235], v[156:159], v[48:51]
	v_mfma_f32_16x16x32_bf16 v[36:39], v[210:213], v[164:167], v[36:39]
	v_mfma_f32_16x16x32_bf16 v[32:35], v[232:235], v[164:167], v[32:35]
	v_mfma_f32_16x16x32_bf16 v[20:23], v[210:213], v[194:197], v[20:23]
	v_mfma_f32_16x16x32_bf16 v[16:19], v[232:235], v[194:197], v[16:19]
	v_mfma_f32_16x16x32_bf16 v[4:7], v[210:213], v[202:205], v[4:7]
	v_mfma_f32_16x16x32_bf16 v[0:3], v[232:235], v[202:205], v[0:3]
	v_mfma_f32_16x16x32_bf16 v[52:55], v[214:217], v[160:163], v[52:55]
	v_mfma_f32_16x16x32_bf16 v[48:51], v[236:239], v[160:163], v[48:51]
	v_mfma_f32_16x16x32_bf16 v[36:39], v[214:217], v[168:171], v[36:39]
	v_mfma_f32_16x16x32_bf16 v[32:35], v[236:239], v[168:171], v[32:35]
	v_mfma_f32_16x16x32_bf16 v[20:23], v[214:217], v[198:201], v[20:23]
	v_mfma_f32_16x16x32_bf16 v[16:19], v[236:239], v[198:201], v[16:19]
	v_mfma_f32_16x16x32_bf16 v[4:7], v[214:217], v[206:209], v[4:7]
	v_mfma_f32_16x16x32_bf16 v[0:3], v[236:239], v[206:209], v[0:3]
	s_add_i32 vcc_lo, vcc_lo, 2
	s_add_u32 s66, s66, 0x100
	s_addc_u32 s67, s67, 0
	s_add_u32 s85, s85, 0x100
	s_addc_u32 s91, s91, 0
	s_cmp_lt_u32 vcc_lo, 14
	s_barrier
	s_cbranch_scc1 .LBB0_134
	s_lshl_b32 s4, s4, 8
	v_mov_b32_e32 v176, v175
	v_mov_b32_e32 v188, v190
	s_add_i32 s4, s4, s77
	s_cmp_gt_i32 s6, 7
	v_add_u32_e32 v148, s4, v176
	v_lshlrev_b32_e32 v128, 2, v188
	v_ashrrev_i32_e32 v129, 31, v128
	v_ashrrev_i32_e32 v149, 31, v148
	v_lshl_add_u64 v[128:129], v[128:129], 2, s[8:9]
	v_lshlrev_b64 v[130:131], 6, v[148:149]
	v_add_u32_e32 v166, 16, v148
	v_lshl_add_u64 v[130:131], v[128:129], 0, v[130:131]
	v_ashrrev_i32_e32 v167, 31, v166
	global_load_dwordx4 v[160:163], v[130:131], off
	v_lshlrev_b64 v[130:131], 6, v[166:167]
	v_lshl_add_u64 v[130:131], v[128:129], 0, v[130:131]
	global_load_dwordx4 v[168:171], v[130:131], off
	v_add_u32_e32 v164, 32, v148
	v_ashrrev_i32_e32 v165, 31, v164
	v_lshlrev_b64 v[130:131], 6, v[164:165]
	v_add_u32_e32 v158, 48, v148
	v_lshl_add_u64 v[130:131], v[128:129], 0, v[130:131]
	v_ashrrev_i32_e32 v159, 31, v158
	global_load_dwordx4 v[194:197], v[130:131], off
	v_lshlrev_b64 v[130:131], 6, v[158:159]
	v_lshl_add_u64 v[130:131], v[128:129], 0, v[130:131]
	global_load_dwordx4 v[198:201], v[130:131], off
	v_add_u32_e32 v156, 0x80, v148
	v_ashrrev_i32_e32 v157, 31, v156
	v_lshlrev_b64 v[130:131], 6, v[156:157]
	v_add_u32_e32 v154, 0x90, v148
	v_lshl_add_u64 v[130:131], v[128:129], 0, v[130:131]
	v_ashrrev_i32_e32 v155, 31, v154
	global_load_dwordx4 v[202:205], v[130:131], off
	v_lshlrev_b64 v[130:131], 6, v[154:155]
	v_add_u32_e32 v152, 0xa0, v148
	v_lshl_add_u64 v[130:131], v[128:129], 0, v[130:131]
	v_ashrrev_i32_e32 v153, 31, v152
	global_load_dwordx4 v[206:209], v[130:131], off
	v_lshlrev_b64 v[130:131], 6, v[152:153]
	v_add_u32_e32 v150, 0xb0, v148
	v_lshl_add_u64 v[130:131], v[128:129], 0, v[130:131]
	v_ashrrev_i32_e32 v151, 31, v150
	global_load_dwordx4 v[132:135], v[130:131], off
	v_lshlrev_b64 v[130:131], 6, v[150:151]
	v_lshl_add_u64 v[128:129], v[128:129], 0, v[130:131]
	global_load_dwordx4 v[128:131], v[128:129], off
	s_cselect_b64 s[66:67], -1, 0
	s_lshl_b32 s7, s6, 8
	s_add_i32 s7, s81, s7
	s_cmp_lt_i32 s6, 8
	s_mov_b64 s[68:69], -1
	s_waitcnt vmcnt(0)
	v_mov_b32_e32 v172, v161
	v_mov_b32_e32 v173, v162
	v_mov_b32_e32 v161, v163
	v_mov_b32_e32 v162, v169
	v_mov_b32_e32 v163, v170
	v_mov_b32_e32 v169, v171
	v_pk_add_f32 v[160:161], v[172:173], v[160:161]
	v_pk_add_f32 v[162:163], v[162:163], v[168:169]
	v_mov_b32_e32 v169, v160
	v_mov_b32_e32 v168, v162
	v_mov_b32_e32 v160, v163
	v_pk_add_f32 v[160:161], v[168:169], v[160:161]
	ds_bpermute_b32 v163, v219, v161
	ds_bpermute_b32 v162, v219, v160
	s_waitcnt lgkmcnt(0)
	v_pk_add_f32 v[160:161], v[160:161], v[162:163]
	ds_bpermute_b32 v163, v218, v161
	ds_bpermute_b32 v162, v218, v160
	s_waitcnt lgkmcnt(0)
	v_pk_add_f32 v[160:161], v[160:161], v[162:163]
	s_nop 0
	v_pk_fma_f32 v[172:173], v[160:161], s[30:31], v[178:179] op_sel_hi:[1,0,0]
	v_mov_b32_e32 v162, v199
	v_mul_f32_e32 v160, 0x4b800000, v173
	v_cmp_gt_f32_e32 vcc, s86, v173
	v_mov_b32_e32 v163, v200
	v_mov_b32_e32 v199, v201
	v_cndmask_b32_e32 v160, v173, v160, vcc
	v_rsq_f32_e32 v160, v160
	v_pk_add_f32 v[162:163], v[162:163], v[198:199]
	v_cmp_gt_f32_e64 s[4:5], s86, v172
	v_mov_b32_e32 v168, v162
	v_mul_f32_e32 v161, 0x45800000, v160
	v_cndmask_b32_e32 v174, v160, v161, vcc
	v_mov_b32_e32 v160, v195
	v_mov_b32_e32 v161, v196
	v_mov_b32_e32 v195, v197
	v_pk_add_f32 v[160:161], v[160:161], v[194:195]
	s_nop 0
	v_mov_b32_e32 v169, v160
	v_mov_b32_e32 v160, v163
	v_pk_add_f32 v[160:161], v[168:169], v[160:161]
	ds_bpermute_b32 v163, v219, v161
	ds_bpermute_b32 v162, v219, v160
	s_waitcnt lgkmcnt(0)
	v_pk_add_f32 v[168:169], v[160:161], v[162:163]
	v_mov_b32_e32 v160, v203
	v_mov_b32_e32 v161, v204
	v_mov_b32_e32 v203, v205
	v_mov_b32_e32 v162, v207
	v_mov_b32_e32 v163, v208
	v_mov_b32_e32 v207, v209
	v_pk_add_f32 v[160:161], v[160:161], v[202:203]
	v_pk_add_f32 v[162:163], v[162:163], v[206:207]
	v_mov_b32_e32 v195, v160
	v_mov_b32_e32 v194, v162
	v_mov_b32_e32 v160, v163
	v_pk_add_f32 v[160:161], v[194:195], v[160:161]
	v_mov_b32_e32 v194, v133
	v_mov_b32_e32 v195, v134
	v_mov_b32_e32 v133, v135
	v_mov_b32_e32 v134, v129
	v_mov_b32_e32 v135, v130
	v_mov_b32_e32 v129, v131
	v_pk_add_f32 v[132:133], v[194:195], v[132:133]
	v_pk_add_f32 v[128:129], v[134:135], v[128:129]
	v_mov_b32_e32 v131, v132
	v_mov_b32_e32 v130, v128
	v_mov_b32_e32 v132, v129
	v_pk_add_f32 v[128:129], v[130:131], v[132:133]
	ds_bpermute_b32 v163, v219, v161
	ds_bpermute_b32 v162, v219, v160
	ds_bpermute_b32 v131, v219, v129
	ds_bpermute_b32 v130, v219, v128
	ds_bpermute_b32 v171, v218, v169
	ds_bpermute_b32 v170, v218, v168
	s_waitcnt lgkmcnt(4)
	v_pk_add_f32 v[160:161], v[160:161], v[162:163]
	ds_bpermute_b32 v163, v218, v161
	s_waitcnt lgkmcnt(3)
	v_pk_add_f32 v[132:133], v[128:129], v[130:131]
	ds_bpermute_b32 v162, v218, v160
	ds_bpermute_b32 v135, v218, v133
	ds_bpermute_b32 v134, v218, v132
	v_lshlrev_b32_e32 v128, 3, v188
	v_add_u32_e32 v130, s7, v128
	v_lshlrev_b64 v[188:189], 11, v[148:149]
	v_ashrrev_i32_e32 v131, 31, v130
	s_cbranch_scc1 .LBB0_137
	v_mul_f32_e32 v196, v120, v174
	v_mul_f32_e32 v197, v121, v174
	v_mul_f32_e32 v198, v122, v174
	v_mul_f32_e32 v199, v123, v174
	v_mul_f32_e32 v129, v124, v174
	v_mul_f32_e32 v149, v125, v174
	v_mul_f32_e32 v173, v126, v174
	v_mul_f32_e32 v193, v127, v174
	v_cvt_pk_bf16_f32 v194, v129, v149
	v_cvt_pk_bf16_f32 v195, v173, v193
	v_cvt_pk_bf16_f32 v196, v196, v197
	v_cvt_pk_bf16_f32 v197, v198, v199
	v_lshl_add_u64 v[198:199], s[12:13], 0, v[188:189]
	v_lshl_add_u64 v[198:199], v[130:131], 1, v[198:199]
	global_store_dwordx4 v[198:199], v[194:197], off
	s_mov_b64 s[68:69], 0
	v_mul_f32_e32 v129, v116, v174
	v_mul_f32_e32 v196, v112, v174
	v_mul_f32_e32 v197, v113, v174
	v_mul_f32_e32 v149, v117, v174
	v_mul_f32_e32 v173, v118, v174
	v_mul_f32_e32 v193, v119, v174
	v_mul_f32_e32 v200, v114, v174
	v_mul_f32_e32 v201, v115, v174
	v_cvt_pk_bf16_f32 v194, v129, v149
	v_cvt_pk_bf16_f32 v195, v173, v193
	v_cvt_pk_bf16_f32 v196, v196, v197
	v_cvt_pk_bf16_f32 v197, v200, v201
	global_store_dwordx4 v[198:199], v[194:197], off offset:256

.LBB0_413:
	s_add_i32 vcc_lo, s62, 2
	s_add_u32 s4, s18, 0x100
	s_addc_u32 s5, s19, 0
	s_add_i32 s28, 0, 0x10000
	v_add_u32_e32 v140, s28, v164
	ds_read_b128 v[128:131], v140
	ds_read_b128 v[132:135], v140 offset:1024
	ds_read_b128 v[136:139], v140 offset:2048
	ds_read_b128 v[140:143], v140 offset:3072
	s_cmp_eq_u32 s13, s62
	s_cselect_b32 s62, s6, s85
	s_cselect_b32 s65, s17, s5
	s_cselect_b32 s64, s16, s4
	s_cselect_b32 s63, s7, s91
	s_add_i32 m0, s69, 0xc000
	ds_read_b128 v[154:157], v165
	ds_read_b128 v[166:169], v165 offset:2048
	ds_read_b128 v[188:191], v165 offset:4096
	ds_read_b128 v[196:199], v165 offset:6144
	ds_read_b128 v[158:161], v165 offset:1024
	ds_read_b128 v[170:173], v165 offset:3072
	ds_read_b128 v[192:195], v165 offset:5120
	ds_read_b128 v[200:203], v165 offset:7168
	global_load_lds_dwordx4 v150, s[18:19]
	s_add_i32 m0, s69, 0xe000
	s_nop 0
	global_load_lds_dwordx4 v152, s[18:19]
	s_waitcnt lgkmcnt(8)
	s_barrier
	s_waitcnt lgkmcnt(7)
	v_mfma_f32_16x16x32_bf16 v[124:127], v[128:131], v[154:157], v[124:127]
	v_mfma_f32_16x16x32_bf16 v[120:123], v[136:139], v[154:157], v[120:123]
	s_waitcnt lgkmcnt(6)
	v_mfma_f32_16x16x32_bf16 v[108:111], v[128:131], v[166:169], v[108:111]
	v_mfma_f32_16x16x32_bf16 v[104:107], v[136:139], v[166:169], v[104:107]
	s_waitcnt lgkmcnt(5)
	v_mfma_f32_16x16x32_bf16 v[92:95], v[128:131], v[188:191], v[92:95]
	v_mfma_f32_16x16x32_bf16 v[88:91], v[136:139], v[188:191], v[88:91]
	s_waitcnt lgkmcnt(4)
	v_mfma_f32_16x16x32_bf16 v[76:79], v[128:131], v[196:199], v[76:79]
	v_mfma_f32_16x16x32_bf16 v[72:75], v[136:139], v[196:199], v[72:75]
	s_waitcnt lgkmcnt(3)
	v_mfma_f32_16x16x32_bf16 v[124:127], v[132:135], v[158:161], v[124:127]
	v_mfma_f32_16x16x32_bf16 v[120:123], v[140:143], v[158:161], v[120:123]
	s_waitcnt lgkmcnt(2)
	v_mfma_f32_16x16x32_bf16 v[108:111], v[132:135], v[170:173], v[108:111]
	v_mfma_f32_16x16x32_bf16 v[104:107], v[140:143], v[170:173], v[104:107]
	s_waitcnt lgkmcnt(1)
	v_mfma_f32_16x16x32_bf16 v[92:95], v[132:135], v[192:195], v[92:95]
	v_mfma_f32_16x16x32_bf16 v[88:91], v[140:143], v[192:195], v[88:91]
	s_waitcnt lgkmcnt(0)
	v_mfma_f32_16x16x32_bf16 v[76:79], v[132:135], v[200:203], v[76:79]
	v_mfma_f32_16x16x32_bf16 v[72:75], v[140:143], v[200:203], v[72:75]
	s_barrier
	s_add_i32 s29, 0, 0x14000
	v_add_u32_e32 v174, s29, v164
	s_add_i32 s18, s28, s68
	ds_read_b128 v[204:207], v174
	ds_read_b128 v[208:211], v174 offset:1024
	ds_read_b128 v[212:215], v174 offset:2048
	ds_read_b128 v[232:235], v174 offset:3072
	s_mov_b32 m0, s18
	s_nop 0
	global_load_lds_dwordx4 v176, s[62:63]
	s_add_i32 m0, s18, 0x2000
	s_nop 0
	global_load_lds_dwordx4 v148, s[62:63]
	s_barrier
	s_waitcnt lgkmcnt(3)
	v_mfma_f32_16x16x32_bf16 v[116:119], v[204:207], v[154:157], v[116:119]
	s_waitcnt lgkmcnt(1)
	v_mfma_f32_16x16x32_bf16 v[112:115], v[212:215], v[154:157], v[112:115]
	v_mfma_f32_16x16x32_bf16 v[100:103], v[204:207], v[166:169], v[100:103]
	v_mfma_f32_16x16x32_bf16 v[96:99], v[212:215], v[166:169], v[96:99]
	v_mfma_f32_16x16x32_bf16 v[84:87], v[204:207], v[188:191], v[84:87]
	v_mfma_f32_16x16x32_bf16 v[80:83], v[212:215], v[188:191], v[80:83]
	v_mfma_f32_16x16x32_bf16 v[68:71], v[204:207], v[196:199], v[68:71]
	v_mfma_f32_16x16x32_bf16 v[64:67], v[212:215], v[196:199], v[64:67]
	v_mfma_f32_16x16x32_bf16 v[116:119], v[208:211], v[158:161], v[116:119]
	s_waitcnt lgkmcnt(0)
	v_mfma_f32_16x16x32_bf16 v[112:115], v[232:235], v[158:161], v[112:115]
	v_mfma_f32_16x16x32_bf16 v[100:103], v[208:211], v[170:173], v[100:103]
	v_mfma_f32_16x16x32_bf16 v[96:99], v[232:235], v[170:173], v[96:99]
	v_mfma_f32_16x16x32_bf16 v[84:87], v[208:211], v[192:195], v[84:87]
	v_mfma_f32_16x16x32_bf16 v[80:83], v[232:235], v[192:195], v[80:83]
	v_mfma_f32_16x16x32_bf16 v[68:71], v[208:211], v[200:203], v[68:71]
	v_mfma_f32_16x16x32_bf16 v[64:67], v[232:235], v[200:203], v[64:67]
	s_mov_b32 m0, s69
	s_barrier
	ds_read_b128 v[154:157], v165 offset:16384
	ds_read_b128 v[166:169], v165 offset:18432
	ds_read_b128 v[188:191], v165 offset:20480
	ds_read_b128 v[196:199], v165 offset:22528
	ds_read_b128 v[158:161], v165 offset:17408
	ds_read_b128 v[170:173], v165 offset:19456
	ds_read_b128 v[192:195], v165 offset:21504
	ds_read_b128 v[200:203], v165 offset:23552
	global_load_lds_dwordx4 v144, s[64:65]
	s_mov_b32 m0, s70
	s_nop 0
	global_load_lds_dwordx4 v146, s[64:65]
	s_barrier
	s_waitcnt lgkmcnt(7)
	v_mfma_f32_16x16x32_bf16 v[60:63], v[128:131], v[154:157], v[60:63]
	v_mfma_f32_16x16x32_bf16 v[56:59], v[136:139], v[154:157], v[56:59]
	s_waitcnt lgkmcnt(6)
	v_mfma_f32_16x16x32_bf16 v[44:47], v[128:131], v[166:169], v[44:47]
	v_mfma_f32_16x16x32_bf16 v[40:43], v[136:139], v[166:169], v[40:43]
	s_waitcnt lgkmcnt(5)
	v_mfma_f32_16x16x32_bf16 v[28:31], v[128:131], v[188:191], v[28:31]
	v_mfma_f32_16x16x32_bf16 v[24:27], v[136:139], v[188:191], v[24:27]
	s_waitcnt lgkmcnt(4)
	v_mfma_f32_16x16x32_bf16 v[12:15], v[128:131], v[196:199], v[12:15]
	v_mfma_f32_16x16x32_bf16 v[8:11], v[136:139], v[196:199], v[8:11]
	s_waitcnt lgkmcnt(3)
	v_mfma_f32_16x16x32_bf16 v[60:63], v[132:135], v[158:161], v[60:63]
	v_mfma_f32_16x16x32_bf16 v[56:59], v[140:143], v[158:161], v[56:59]
	s_waitcnt lgkmcnt(2)
	v_mfma_f32_16x16x32_bf16 v[44:47], v[132:135], v[170:173], v[44:47]
	v_mfma_f32_16x16x32_bf16 v[40:43], v[140:143], v[170:173], v[40:43]
	s_waitcnt lgkmcnt(1)
	v_mfma_f32_16x16x32_bf16 v[28:31], v[132:135], v[192:195], v[28:31]
	v_mfma_f32_16x16x32_bf16 v[24:27], v[140:143], v[192:195], v[24:27]
	s_waitcnt lgkmcnt(0)
	v_mfma_f32_16x16x32_bf16 v[12:15], v[132:135], v[200:203], v[12:15]
	v_mfma_f32_16x16x32_bf16 v[8:11], v[140:143], v[200:203], v[8:11]
	s_barrier
	s_add_u32 s18, s62, 0x18000
	s_addc_u32 s19, s63, 0
	s_add_i32 s28, s29, s68
	s_mov_b32 m0, s28
	s_nop 0
	global_load_lds_dwordx4 v176, s[18:19]
	s_add_i32 m0, s28, 0x2000
	s_nop 0
	global_load_lds_dwordx4 v148, s[18:19]
	s_waitcnt vmcnt(6)
	s_barrier
	v_mfma_f32_16x16x32_bf16 v[52:55], v[204:207], v[154:157], v[52:55]
	v_mfma_f32_16x16x32_bf16 v[48:51], v[212:215], v[154:157], v[48:51]
	v_mfma_f32_16x16x32_bf16 v[36:39], v[204:207], v[166:169], v[36:39]
	v_mfma_f32_16x16x32_bf16 v[32:35], v[212:215], v[166:169], v[32:35]
	v_mfma_f32_16x16x32_bf16 v[20:23], v[204:207], v[188:191], v[20:23]
	v_mfma_f32_16x16x32_bf16 v[16:19], v[212:215], v[188:191], v[16:19]
	v_mfma_f32_16x16x32_bf16 v[4:7], v[204:207], v[196:199], v[4:7]
	v_mfma_f32_16x16x32_bf16 v[0:3], v[212:215], v[196:199], v[0:3]
	v_mfma_f32_16x16x32_bf16 v[52:55], v[208:211], v[158:161], v[52:55]
	v_mfma_f32_16x16x32_bf16 v[48:51], v[232:235], v[158:161], v[48:51]
	v_mfma_f32_16x16x32_bf16 v[36:39], v[208:211], v[170:173], v[36:39]
	v_mfma_f32_16x16x32_bf16 v[32:35], v[232:235], v[170:173], v[32:35]
	v_mfma_f32_16x16x32_bf16 v[20:23], v[208:211], v[192:195], v[20:23]
	v_mfma_f32_16x16x32_bf16 v[16:19], v[232:235], v[192:195], v[16:19]
	v_mfma_f32_16x16x32_bf16 v[4:7], v[208:211], v[200:203], v[4:7]
	v_mfma_f32_16x16x32_bf16 v[0:3], v[232:235], v[200:203], v[0:3]
	s_add_i32 s28, 0, 0x18000
	v_add_u32_e32 v140, s28, v164
	s_barrier
	ds_read_b128 v[128:131], v140
	ds_read_b128 v[132:135], v140 offset:1024
	ds_read_b128 v[136:139], v140 offset:2048
	ds_read_b128 v[140:143], v140 offset:3072
	s_add_u32 s18, s64, 0x18000
	s_addc_u32 s19, s65, 0
	s_mov_b32 m0, s71
	ds_read_b128 v[154:157], v165 offset:32768
	ds_read_b128 v[166:169], v165 offset:34816
	ds_read_b128 v[188:191], v165 offset:36864
	ds_read_b128 v[196:199], v165 offset:38912
	ds_read_b128 v[158:161], v165 offset:33792
	ds_read_b128 v[170:173], v165 offset:35840
	ds_read_b128 v[192:195], v165 offset:37888
	ds_read_b128 v[200:203], v165 offset:39936
	global_load_lds_dwordx4 v144, s[18:19]
	s_mov_b32 m0, s72
	s_nop 0
	global_load_lds_dwordx4 v146, s[18:19]
	s_waitcnt lgkmcnt(8)
	s_barrier
	s_waitcnt lgkmcnt(7)
	v_mfma_f32_16x16x32_bf16 v[124:127], v[128:131], v[154:157], v[124:127]
	v_mfma_f32_16x16x32_bf16 v[120:123], v[136:139], v[154:157], v[120:123]
	s_waitcnt lgkmcnt(6)
	v_mfma_f32_16x16x32_bf16 v[108:111], v[128:131], v[166:169], v[108:111]
	v_mfma_f32_16x16x32_bf16 v[104:107], v[136:139], v[166:169], v[104:107]
	s_waitcnt lgkmcnt(5)
	v_mfma_f32_16x16x32_bf16 v[92:95], v[128:131], v[188:191], v[92:95]
	v_mfma_f32_16x16x32_bf16 v[88:91], v[136:139], v[188:191], v[88:91]
	s_waitcnt lgkmcnt(4)
	v_mfma_f32_16x16x32_bf16 v[76:79], v[128:131], v[196:199], v[76:79]
	v_mfma_f32_16x16x32_bf16 v[72:75], v[136:139], v[196:199], v[72:75]
	s_waitcnt lgkmcnt(3)
	v_mfma_f32_16x16x32_bf16 v[124:127], v[132:135], v[158:161], v[124:127]
	v_mfma_f32_16x16x32_bf16 v[120:123], v[140:143], v[158:161], v[120:123]
	s_waitcnt lgkmcnt(2)
	v_mfma_f32_16x16x32_bf16 v[108:111], v[132:135], v[170:173], v[108:111]
	v_mfma_f32_16x16x32_bf16 v[104:107], v[140:143], v[170:173], v[104:107]
	s_waitcnt lgkmcnt(1)
	v_mfma_f32_16x16x32_bf16 v[92:95], v[132:135], v[192:195], v[92:95]
	v_mfma_f32_16x16x32_bf16 v[88:91], v[140:143], v[192:195], v[88:91]
	s_waitcnt lgkmcnt(0)
	v_mfma_f32_16x16x32_bf16 v[76:79], v[132:135], v[200:203], v[76:79]
	v_mfma_f32_16x16x32_bf16 v[72:75], v[140:143], v[200:203], v[72:75]
	s_barrier
	s_add_i32 s29, 0, 0x1c000
	s_add_i32 s18, s28, s68
	v_add_u32_e32 v232, s29, v164
	s_mov_b32 m0, s18
	ds_read_b128 v[204:207], v232
	ds_read_b128 v[208:211], v232 offset:1024
	ds_read_b128 v[212:215], v232 offset:2048
	ds_read_b128 v[232:235], v232 offset:3072
	s_add_u32 s98, s62, 0x80
	s_addc_u32 s99, s63, 0
	global_load_lds_dwordx4 v176, s[98:99]
	s_add_i32 m0, s18, 0x2000
	s_nop 0
	global_load_lds_dwordx4 v148, s[98:99]
	s_barrier
	s_waitcnt lgkmcnt(3)
	v_mfma_f32_16x16x32_bf16 v[116:119], v[204:207], v[154:157], v[116:119]
	s_waitcnt lgkmcnt(1)
	v_mfma_f32_16x16x32_bf16 v[112:115], v[212:215], v[154:157], v[112:115]
	v_mfma_f32_16x16x32_bf16 v[100:103], v[204:207], v[166:169], v[100:103]
	v_mfma_f32_16x16x32_bf16 v[96:99], v[212:215], v[166:169], v[96:99]
	v_mfma_f32_16x16x32_bf16 v[84:87], v[204:207], v[188:191], v[84:87]
	v_mfma_f32_16x16x32_bf16 v[80:83], v[212:215], v[188:191], v[80:83]
	v_mfma_f32_16x16x32_bf16 v[68:71], v[204:207], v[196:199], v[68:71]
	v_mfma_f32_16x16x32_bf16 v[64:67], v[212:215], v[196:199], v[64:67]
	v_mfma_f32_16x16x32_bf16 v[116:119], v[208:211], v[158:161], v[116:119]
	s_waitcnt lgkmcnt(0)
	v_mfma_f32_16x16x32_bf16 v[112:115], v[232:235], v[158:161], v[112:115]
	v_mfma_f32_16x16x32_bf16 v[100:103], v[208:211], v[170:173], v[100:103]
	v_mfma_f32_16x16x32_bf16 v[96:99], v[232:235], v[170:173], v[96:99]
	v_mfma_f32_16x16x32_bf16 v[84:87], v[208:211], v[192:195], v[84:87]
	v_mfma_f32_16x16x32_bf16 v[80:83], v[232:235], v[192:195], v[80:83]
	v_mfma_f32_16x16x32_bf16 v[68:71], v[208:211], v[200:203], v[68:71]
	v_mfma_f32_16x16x32_bf16 v[64:67], v[232:235], v[200:203], v[64:67]
	s_mov_b32 m0, s75
	s_barrier
	ds_read_b128 v[154:157], v165 offset:49152
	ds_read_b128 v[166:169], v165 offset:51200
	ds_read_b128 v[188:191], v165 offset:53248
	ds_read_b128 v[196:199], v165 offset:55296
	ds_read_b128 v[158:161], v165 offset:50176
	ds_read_b128 v[170:173], v165 offset:52224
	ds_read_b128 v[192:195], v165 offset:54272
	ds_read_b128 v[200:203], v165 offset:56320
	s_add_u32 s98, s64, 0x80
	s_addc_u32 s99, s65, 0
	global_load_lds_dwordx4 v144, s[98:99]
	s_mov_b32 m0, s76
	s_nop 0
	global_load_lds_dwordx4 v146, s[98:99]
	s_barrier
	s_waitcnt lgkmcnt(7)
	v_mfma_f32_16x16x32_bf16 v[60:63], v[128:131], v[154:157], v[60:63]
	v_mfma_f32_16x16x32_bf16 v[56:59], v[136:139], v[154:157], v[56:59]
	s_waitcnt lgkmcnt(6)
	v_mfma_f32_16x16x32_bf16 v[44:47], v[128:131], v[166:169], v[44:47]
	v_mfma_f32_16x16x32_bf16 v[40:43], v[136:139], v[166:169], v[40:43]
	s_waitcnt lgkmcnt(5)
	v_mfma_f32_16x16x32_bf16 v[28:31], v[128:131], v[188:191], v[28:31]
	v_mfma_f32_16x16x32_bf16 v[24:27], v[136:139], v[188:191], v[24:27]
	s_waitcnt lgkmcnt(4)
	v_mfma_f32_16x16x32_bf16 v[12:15], v[128:131], v[196:199], v[12:15]
	v_mfma_f32_16x16x32_bf16 v[8:11], v[136:139], v[196:199], v[8:11]
	s_waitcnt lgkmcnt(3)
	v_mfma_f32_16x16x32_bf16 v[60:63], v[132:135], v[158:161], v[60:63]
	v_mfma_f32_16x16x32_bf16 v[56:59], v[140:143], v[158:161], v[56:59]
	s_waitcnt lgkmcnt(2)
	v_mfma_f32_16x16x32_bf16 v[44:47], v[132:135], v[170:173], v[44:47]
	v_mfma_f32_16x16x32_bf16 v[40:43], v[140:143], v[170:173], v[40:43]
	s_waitcnt lgkmcnt(1)
	v_mfma_f32_16x16x32_bf16 v[28:31], v[132:135], v[192:195], v[28:31]
	v_mfma_f32_16x16x32_bf16 v[24:27], v[140:143], v[192:195], v[24:27]
	s_waitcnt lgkmcnt(0)
	v_mfma_f32_16x16x32_bf16 v[12:15], v[132:135], v[200:203], v[12:15]
	v_mfma_f32_16x16x32_bf16 v[8:11], v[140:143], v[200:203], v[8:11]
	s_barrier
	s_add_u32 s18, s62, 0x18080
	s_addc_u32 s19, s63, 0
	s_add_i32 s28, s29, s68
	s_mov_b32 m0, s28
	s_nop 0
	global_load_lds_dwordx4 v176, s[18:19]
	s_add_i32 m0, s28, 0x2000
	s_nop 0
	global_load_lds_dwordx4 v148, s[18:19]
	s_waitcnt vmcnt(6)
	s_barrier
	v_mfma_f32_16x16x32_bf16 v[52:55], v[204:207], v[154:157], v[52:55]
	v_mfma_f32_16x16x32_bf16 v[48:51], v[212:215], v[154:157], v[48:51]
	v_mfma_f32_16x16x32_bf16 v[36:39], v[204:207], v[166:169], v[36:39]
	v_mfma_f32_16x16x32_bf16 v[32:35], v[212:215], v[166:169], v[32:35]
	v_mfma_f32_16x16x32_bf16 v[20:23], v[204:207], v[188:191], v[20:23]
	v_mfma_f32_16x16x32_bf16 v[16:19], v[212:215], v[188:191], v[16:19]
	v_mfma_f32_16x16x32_bf16 v[4:7], v[204:207], v[196:199], v[4:7]
	v_mfma_f32_16x16x32_bf16 v[0:3], v[212:215], v[196:199], v[0:3]
	v_mfma_f32_16x16x32_bf16 v[52:55], v[208:211], v[158:161], v[52:55]
	v_mfma_f32_16x16x32_bf16 v[48:51], v[232:235], v[158:161], v[48:51]
	v_mfma_f32_16x16x32_bf16 v[36:39], v[208:211], v[170:173], v[36:39]
	v_mfma_f32_16x16x32_bf16 v[32:35], v[232:235], v[170:173], v[32:35]
	v_mfma_f32_16x16x32_bf16 v[20:23], v[208:211], v[192:195], v[20:23]
	v_mfma_f32_16x16x32_bf16 v[16:19], v[232:235], v[192:195], v[16:19]
	v_mfma_f32_16x16x32_bf16 v[4:7], v[208:211], v[200:203], v[4:7]
	v_mfma_f32_16x16x32_bf16 v[0:3], v[232:235], v[200:203], v[0:3]
	s_add_u32 s85, s85, 0x100
	s_addc_u32 s91, s91, 0
	s_cmp_lt_i32 vcc_lo, s67
	s_mov_b64 s[18:19], s[4:5]
	s_mov_b32 s62, vcc_lo
	s_barrier
	s_cbranch_scc1 .LBB0_413
	s_ashr_i32 s4, s66, 2
	v_mov_b32_e32 v128, v163
	v_mov_b32_e32 v166, v162
	s_cmp_eq_u32 s4, 2
	s_cbranch_scc1 .LBB0_416
	s_mul_i32 s13, s4, 0x2280000
	s_mul_hi_i32 s5, s4, 0x2280000
	s_add_u32 s18, s13, 0x5858000
	s_addc_u32 s19, s5, 0
	s_mov_b32 s62, 1.0
	s_branch .LBB0_417

.LBB0_505:
	s_add_u32 s6, s4, 0xfff80080
	s_addc_u32 s7, s5, -1
	s_add_i32 s28, 0, 0x10000
	v_add_u32_e32 v154, s28, v144
	ds_read_b128 v[138:141], v154
	ds_read_b128 v[146:149], v154 offset:1024
	ds_read_b128 v[150:153], v154 offset:2048
	ds_read_b128 v[154:157], v154 offset:3072
	s_cmp_eq_u32 s72, 28
	s_cselect_b32 s9, s10, s7
	s_cselect_b32 s8, s11, s6
	s_cselect_b32 s7, s63, s71
	s_cselect_b32 s6, s65, s70
	s_add_i32 m0, s17, 0xc000
	ds_read_b128 v[158:161], v145
	ds_read_b128 v[166:169], v145 offset:2048
	ds_read_b128 v[188:191], v145 offset:4096
	ds_read_b128 v[196:199], v145 offset:6144
	ds_read_b128 v[162:165], v145 offset:1024
	ds_read_b128 v[170:173], v145 offset:3072
	ds_read_b128 v[192:195], v145 offset:5120
	ds_read_b128 v[200:203], v145 offset:7168
	global_load_lds_dwordx4 v134, s[4:5]
	s_add_i32 m0, s17, 0xe000
	s_nop 0
	global_load_lds_dwordx4 v136, s[4:5]
	s_waitcnt lgkmcnt(8)
	s_barrier
	s_waitcnt lgkmcnt(7)
	v_mfma_f32_16x16x32_bf16 v[124:127], v[138:141], v[158:161], v[124:127]
	v_mfma_f32_16x16x32_bf16 v[120:123], v[150:153], v[158:161], v[120:123]
	s_waitcnt lgkmcnt(6)
	v_mfma_f32_16x16x32_bf16 v[116:119], v[138:141], v[166:169], v[116:119]
	v_mfma_f32_16x16x32_bf16 v[108:111], v[150:153], v[166:169], v[108:111]
	s_waitcnt lgkmcnt(5)
	v_mfma_f32_16x16x32_bf16 v[100:103], v[138:141], v[188:191], v[100:103]
	v_mfma_f32_16x16x32_bf16 v[92:95], v[150:153], v[188:191], v[92:95]
	s_waitcnt lgkmcnt(4)
	v_mfma_f32_16x16x32_bf16 v[84:87], v[138:141], v[196:199], v[84:87]
	v_mfma_f32_16x16x32_bf16 v[76:79], v[150:153], v[196:199], v[76:79]
	s_waitcnt lgkmcnt(3)
	v_mfma_f32_16x16x32_bf16 v[124:127], v[146:149], v[162:165], v[124:127]
	v_mfma_f32_16x16x32_bf16 v[120:123], v[154:157], v[162:165], v[120:123]
	s_waitcnt lgkmcnt(2)
	v_mfma_f32_16x16x32_bf16 v[116:119], v[146:149], v[170:173], v[116:119]
	v_mfma_f32_16x16x32_bf16 v[108:111], v[154:157], v[170:173], v[108:111]
	s_waitcnt lgkmcnt(1)
	v_mfma_f32_16x16x32_bf16 v[100:103], v[146:149], v[192:195], v[100:103]
	v_mfma_f32_16x16x32_bf16 v[92:95], v[154:157], v[192:195], v[92:95]
	s_waitcnt lgkmcnt(0)
	v_mfma_f32_16x16x32_bf16 v[84:87], v[146:149], v[200:203], v[84:87]
	v_mfma_f32_16x16x32_bf16 v[76:79], v[154:157], v[200:203], v[76:79]
	s_barrier
	s_add_i32 s29, 0, 0x14000
	v_add_u32_e32 v174, s29, v144
	s_add_i32 s28, s28, s77
	ds_read_b128 v[204:207], v174
	ds_read_b128 v[208:211], v174 offset:1024
	ds_read_b128 v[212:215], v174 offset:2048
	ds_read_b128 v[232:235], v174 offset:3072
	s_mov_b32 m0, s28
	s_nop 0
	global_load_lds_dwordx4 v176, s[6:7]
	s_add_i32 m0, s28, 0x2000
	s_nop 0
	global_load_lds_dwordx4 v132, s[6:7]
	s_barrier
	s_waitcnt lgkmcnt(3)
	v_mfma_f32_16x16x32_bf16 v[112:115], v[204:207], v[158:161], v[112:115]
	s_waitcnt lgkmcnt(1)
	v_mfma_f32_16x16x32_bf16 v[104:107], v[212:215], v[158:161], v[104:107]
	v_mfma_f32_16x16x32_bf16 v[96:99], v[204:207], v[166:169], v[96:99]
	v_mfma_f32_16x16x32_bf16 v[88:91], v[212:215], v[166:169], v[88:91]
	v_mfma_f32_16x16x32_bf16 v[80:83], v[204:207], v[188:191], v[80:83]
	v_mfma_f32_16x16x32_bf16 v[72:75], v[212:215], v[188:191], v[72:75]
	v_mfma_f32_16x16x32_bf16 v[68:71], v[204:207], v[196:199], v[68:71]
	v_mfma_f32_16x16x32_bf16 v[64:67], v[212:215], v[196:199], v[64:67]
	v_mfma_f32_16x16x32_bf16 v[112:115], v[208:211], v[162:165], v[112:115]
	s_waitcnt lgkmcnt(0)
	v_mfma_f32_16x16x32_bf16 v[104:107], v[232:235], v[162:165], v[104:107]
	v_mfma_f32_16x16x32_bf16 v[96:99], v[208:211], v[170:173], v[96:99]
	v_mfma_f32_16x16x32_bf16 v[88:91], v[232:235], v[170:173], v[88:91]
	v_mfma_f32_16x16x32_bf16 v[80:83], v[208:211], v[192:195], v[80:83]
	v_mfma_f32_16x16x32_bf16 v[72:75], v[232:235], v[192:195], v[72:75]
	v_mfma_f32_16x16x32_bf16 v[68:71], v[208:211], v[200:203], v[68:71]
	v_mfma_f32_16x16x32_bf16 v[64:67], v[232:235], v[200:203], v[64:67]
	s_mov_b32 m0, s17
	v_lshl_add_u64 v[236:237], s[8:9], 0, v[128:129]
	s_barrier
	ds_read_b128 v[158:161], v145 offset:16384
	ds_read_b128 v[166:169], v145 offset:18432
	ds_read_b128 v[188:191], v145 offset:20480
	ds_read_b128 v[196:199], v145 offset:22528
	ds_read_b128 v[162:165], v145 offset:17408
	ds_read_b128 v[170:173], v145 offset:19456
	ds_read_b128 v[192:195], v145 offset:21504
	ds_read_b128 v[200:203], v145 offset:23552
	global_load_lds_dwordx4 v128, s[8:9]
	v_lshl_add_u64 v[238:239], s[8:9], 0, v[130:131]
	s_mov_b32 m0, s19
	s_nop 0
	global_load_lds_dwordx4 v130, s[8:9]
	s_barrier
	s_waitcnt lgkmcnt(7)
	v_mfma_f32_16x16x32_bf16 v[60:63], v[138:141], v[158:161], v[60:63]
	v_mfma_f32_16x16x32_bf16 v[56:59], v[150:153], v[158:161], v[56:59]
	s_waitcnt lgkmcnt(6)
	v_mfma_f32_16x16x32_bf16 v[52:55], v[138:141], v[166:169], v[52:55]
	v_mfma_f32_16x16x32_bf16 v[44:47], v[150:153], v[166:169], v[44:47]
	s_waitcnt lgkmcnt(5)
	v_mfma_f32_16x16x32_bf16 v[36:39], v[138:141], v[188:191], v[36:39]
	v_mfma_f32_16x16x32_bf16 v[28:31], v[150:153], v[188:191], v[28:31]
	s_waitcnt lgkmcnt(4)
	v_mfma_f32_16x16x32_bf16 v[20:23], v[138:141], v[196:199], v[20:23]
	v_mfma_f32_16x16x32_bf16 v[12:15], v[150:153], v[196:199], v[12:15]
	s_waitcnt lgkmcnt(3)
	v_mfma_f32_16x16x32_bf16 v[60:63], v[146:149], v[162:165], v[60:63]
	v_mfma_f32_16x16x32_bf16 v[56:59], v[154:157], v[162:165], v[56:59]
	s_waitcnt lgkmcnt(2)
	v_mfma_f32_16x16x32_bf16 v[52:55], v[146:149], v[170:173], v[52:55]
	v_mfma_f32_16x16x32_bf16 v[44:47], v[154:157], v[170:173], v[44:47]
	s_waitcnt lgkmcnt(1)
	v_mfma_f32_16x16x32_bf16 v[36:39], v[146:149], v[192:195], v[36:39]
	v_mfma_f32_16x16x32_bf16 v[28:31], v[154:157], v[192:195], v[28:31]
	s_waitcnt lgkmcnt(0)
	v_mfma_f32_16x16x32_bf16 v[20:23], v[146:149], v[200:203], v[20:23]
	v_mfma_f32_16x16x32_bf16 v[12:15], v[154:157], v[200:203], v[12:15]
	s_barrier
	s_add_u32 vcc_lo, s6, 0x80000
	s_addc_u32 vcc_hi, s7, 0
	s_add_i32 s28, s29, s77
	v_lshl_add_u64 v[138:139], vcc, 0, v[176:177]
	s_mov_b32 m0, s28
	s_nop 0
	global_load_lds_dwordx4 v[138:139], off
	v_lshl_add_u64 v[138:139], vcc, 0, v[132:133]
	s_add_i32 m0, s28, 0x2000
	s_nop 0
	global_load_lds_dwordx4 v[138:139], off
	s_waitcnt vmcnt(6)
	s_barrier
	v_mfma_f32_16x16x32_bf16 v[48:51], v[204:207], v[158:161], v[48:51]
	v_mfma_f32_16x16x32_bf16 v[40:43], v[212:215], v[158:161], v[40:43]
	v_mfma_f32_16x16x32_bf16 v[32:35], v[204:207], v[166:169], v[32:35]
	v_mfma_f32_16x16x32_bf16 v[24:27], v[212:215], v[166:169], v[24:27]
	v_mfma_f32_16x16x32_bf16 v[16:19], v[204:207], v[188:191], v[16:19]
	v_mfma_f32_16x16x32_bf16 v[8:11], v[212:215], v[188:191], v[8:11]
	v_mfma_f32_16x16x32_bf16 v[4:7], v[204:207], v[196:199], v[4:7]
	v_mfma_f32_16x16x32_bf16 v[0:3], v[212:215], v[196:199], v[0:3]
	v_mfma_f32_16x16x32_bf16 v[48:51], v[208:211], v[162:165], v[48:51]
	v_mfma_f32_16x16x32_bf16 v[40:43], v[232:235], v[162:165], v[40:43]
	v_mfma_f32_16x16x32_bf16 v[32:35], v[208:211], v[170:173], v[32:35]
	v_mfma_f32_16x16x32_bf16 v[24:27], v[232:235], v[170:173], v[24:27]
	v_mfma_f32_16x16x32_bf16 v[16:19], v[208:211], v[192:195], v[16:19]
	v_mfma_f32_16x16x32_bf16 v[8:11], v[232:235], v[192:195], v[8:11]
	v_mfma_f32_16x16x32_bf16 v[4:7], v[208:211], v[200:203], v[4:7]
	v_mfma_f32_16x16x32_bf16 v[0:3], v[232:235], v[200:203], v[0:3]
	s_add_i32 s28, 0, 0x18000
	v_add_u32_e32 v154, s28, v144
	s_barrier
	ds_read_b128 v[138:141], v154
	ds_read_b128 v[146:149], v154 offset:1024
	ds_read_b128 v[150:153], v154 offset:2048
	ds_read_b128 v[154:157], v154 offset:3072
	s_add_u32 s8, s8, 0x80000
	s_addc_u32 s9, s9, 0
	s_mov_b32 m0, s78
	ds_read_b128 v[158:161], v145 offset:32768
	ds_read_b128 v[166:169], v145 offset:34816
	ds_read_b128 v[188:191], v145 offset:36864
	ds_read_b128 v[196:199], v145 offset:38912
	ds_read_b128 v[162:165], v145 offset:33792
	ds_read_b128 v[170:173], v145 offset:35840
	ds_read_b128 v[192:195], v145 offset:37888
	ds_read_b128 v[200:203], v145 offset:39936
	global_load_lds_dwordx4 v128, s[8:9]
	s_mov_b32 m0, s79
	s_nop 0
	global_load_lds_dwordx4 v130, s[8:9]
	s_waitcnt lgkmcnt(8)
	s_barrier
	s_waitcnt lgkmcnt(7)
	v_mfma_f32_16x16x32_bf16 v[124:127], v[138:141], v[158:161], v[124:127]
	v_mfma_f32_16x16x32_bf16 v[120:123], v[150:153], v[158:161], v[120:123]
	s_waitcnt lgkmcnt(6)
	v_mfma_f32_16x16x32_bf16 v[116:119], v[138:141], v[166:169], v[116:119]
	v_mfma_f32_16x16x32_bf16 v[108:111], v[150:153], v[166:169], v[108:111]
	s_waitcnt lgkmcnt(5)
	v_mfma_f32_16x16x32_bf16 v[100:103], v[138:141], v[188:191], v[100:103]
	v_mfma_f32_16x16x32_bf16 v[92:95], v[150:153], v[188:191], v[92:95]
	s_waitcnt lgkmcnt(4)
	v_mfma_f32_16x16x32_bf16 v[84:87], v[138:141], v[196:199], v[84:87]
	v_mfma_f32_16x16x32_bf16 v[76:79], v[150:153], v[196:199], v[76:79]
	s_waitcnt lgkmcnt(3)
	v_mfma_f32_16x16x32_bf16 v[124:127], v[146:149], v[162:165], v[124:127]
	v_mfma_f32_16x16x32_bf16 v[120:123], v[154:157], v[162:165], v[120:123]
	s_waitcnt lgkmcnt(2)
	v_mfma_f32_16x16x32_bf16 v[116:119], v[146:149], v[170:173], v[116:119]
	v_mfma_f32_16x16x32_bf16 v[108:111], v[154:157], v[170:173], v[108:111]
	s_waitcnt lgkmcnt(1)
	v_mfma_f32_16x16x32_bf16 v[100:103], v[146:149], v[192:195], v[100:103]
	v_mfma_f32_16x16x32_bf16 v[92:95], v[154:157], v[192:195], v[92:95]
	s_waitcnt lgkmcnt(0)
	v_mfma_f32_16x16x32_bf16 v[84:87], v[146:149], v[200:203], v[84:87]
	v_mfma_f32_16x16x32_bf16 v[76:79], v[154:157], v[200:203], v[76:79]
	s_barrier
	s_add_i32 s8, 0, 0x1c000
	s_add_i32 s9, s28, s77
	v_add_u32_e32 v232, s8, v144
	s_mov_b32 m0, s9
	ds_read_b128 v[204:207], v232
	ds_read_b128 v[208:211], v232 offset:1024
	ds_read_b128 v[212:215], v232 offset:2048
	ds_read_b128 v[232:235], v232 offset:3072
	s_add_u32 s98, s6, 0x80
	s_addc_u32 s99, s7, 0
	global_load_lds_dwordx4 v176, s[98:99]
	s_add_i32 m0, s9, 0x2000
	s_nop 0
	global_load_lds_dwordx4 v132, s[98:99]
	s_barrier
	s_waitcnt lgkmcnt(3)
	v_mfma_f32_16x16x32_bf16 v[112:115], v[204:207], v[158:161], v[112:115]
	s_waitcnt lgkmcnt(1)
	v_mfma_f32_16x16x32_bf16 v[104:107], v[212:215], v[158:161], v[104:107]
	v_mfma_f32_16x16x32_bf16 v[96:99], v[204:207], v[166:169], v[96:99]
	v_mfma_f32_16x16x32_bf16 v[88:91], v[212:215], v[166:169], v[88:91]
	v_mfma_f32_16x16x32_bf16 v[80:83], v[204:207], v[188:191], v[80:83]
	v_mfma_f32_16x16x32_bf16 v[72:75], v[212:215], v[188:191], v[72:75]
	v_mfma_f32_16x16x32_bf16 v[68:71], v[204:207], v[196:199], v[68:71]
	v_mfma_f32_16x16x32_bf16 v[64:67], v[212:215], v[196:199], v[64:67]
	v_mfma_f32_16x16x32_bf16 v[112:115], v[208:211], v[162:165], v[112:115]
	s_waitcnt lgkmcnt(0)
	v_mfma_f32_16x16x32_bf16 v[104:107], v[232:235], v[162:165], v[104:107]
	v_mfma_f32_16x16x32_bf16 v[96:99], v[208:211], v[170:173], v[96:99]
	v_mfma_f32_16x16x32_bf16 v[88:91], v[232:235], v[170:173], v[88:91]
	v_mfma_f32_16x16x32_bf16 v[80:83], v[208:211], v[192:195], v[80:83]
	v_mfma_f32_16x16x32_bf16 v[72:75], v[232:235], v[192:195], v[72:75]
	v_mfma_f32_16x16x32_bf16 v[68:71], v[208:211], v[200:203], v[68:71]
	v_mfma_f32_16x16x32_bf16 v[64:67], v[232:235], v[200:203], v[64:67]
	s_mov_b32 m0, s82
	v_lshl_add_u64 v[174:175], v[236:237], 0, s[40:41]
	s_barrier
	ds_read_b128 v[158:161], v145 offset:49152
	ds_read_b128 v[166:169], v145 offset:51200
	ds_read_b128 v[188:191], v145 offset:53248
	ds_read_b128 v[196:199], v145 offset:55296
	ds_read_b128 v[162:165], v145 offset:50176
	ds_read_b128 v[170:173], v145 offset:52224
	ds_read_b128 v[192:195], v145 offset:54272
	ds_read_b128 v[200:203], v145 offset:56320
	global_load_lds_dwordx4 v[174:175], off
	v_lshl_add_u64 v[174:175], v[238:239], 0, s[40:41]
	s_mov_b32 m0, s83
	s_nop 0
	global_load_lds_dwordx4 v[174:175], off
	s_barrier
	s_waitcnt lgkmcnt(7)
	v_mfma_f32_16x16x32_bf16 v[60:63], v[138:141], v[158:161], v[60:63]
	v_mfma_f32_16x16x32_bf16 v[56:59], v[150:153], v[158:161], v[56:59]
	s_waitcnt lgkmcnt(6)
	v_mfma_f32_16x16x32_bf16 v[52:55], v[138:141], v[166:169], v[52:55]
	v_mfma_f32_16x16x32_bf16 v[44:47], v[150:153], v[166:169], v[44:47]
	s_waitcnt lgkmcnt(5)
	v_mfma_f32_16x16x32_bf16 v[36:39], v[138:141], v[188:191], v[36:39]
	v_mfma_f32_16x16x32_bf16 v[28:31], v[150:153], v[188:191], v[28:31]
	s_waitcnt lgkmcnt(4)
	v_mfma_f32_16x16x32_bf16 v[20:23], v[138:141], v[196:199], v[20:23]
	v_mfma_f32_16x16x32_bf16 v[12:15], v[150:153], v[196:199], v[12:15]
	s_waitcnt lgkmcnt(3)
	v_mfma_f32_16x16x32_bf16 v[60:63], v[146:149], v[162:165], v[60:63]
	v_mfma_f32_16x16x32_bf16 v[56:59], v[154:157], v[162:165], v[56:59]
	s_waitcnt lgkmcnt(2)
	v_mfma_f32_16x16x32_bf16 v[52:55], v[146:149], v[170:173], v[52:55]
	v_mfma_f32_16x16x32_bf16 v[44:47], v[154:157], v[170:173], v[44:47]
	s_waitcnt lgkmcnt(1)
	v_mfma_f32_16x16x32_bf16 v[36:39], v[146:149], v[192:195], v[36:39]
	v_mfma_f32_16x16x32_bf16 v[28:31], v[154:157], v[192:195], v[28:31]
	s_waitcnt lgkmcnt(0)
	v_mfma_f32_16x16x32_bf16 v[20:23], v[146:149], v[200:203], v[20:23]
	v_mfma_f32_16x16x32_bf16 v[12:15], v[154:157], v[200:203], v[12:15]
	s_barrier
	s_add_u32 s6, s6, 0x80080
	s_addc_u32 s7, s7, 0
	s_add_i32 s8, s8, s77
	s_mov_b32 m0, s8
	s_nop 0
	global_load_lds_dwordx4 v176, s[6:7]
	s_add_i32 m0, s8, 0x2000
	s_nop 0
	global_load_lds_dwordx4 v132, s[6:7]
	s_waitcnt vmcnt(6)
	s_barrier
	v_mfma_f32_16x16x32_bf16 v[48:51], v[204:207], v[158:161], v[48:51]
	v_mfma_f32_16x16x32_bf16 v[40:43], v[212:215], v[158:161], v[40:43]
	v_mfma_f32_16x16x32_bf16 v[32:35], v[204:207], v[166:169], v[32:35]
	v_mfma_f32_16x16x32_bf16 v[24:27], v[212:215], v[166:169], v[24:27]
	v_mfma_f32_16x16x32_bf16 v[16:19], v[204:207], v[188:191], v[16:19]
	v_mfma_f32_16x16x32_bf16 v[8:11], v[212:215], v[188:191], v[8:11]
	v_mfma_f32_16x16x32_bf16 v[4:7], v[204:207], v[196:199], v[4:7]
	v_mfma_f32_16x16x32_bf16 v[0:3], v[212:215], v[196:199], v[0:3]
	v_mfma_f32_16x16x32_bf16 v[48:51], v[208:211], v[162:165], v[48:51]
	v_mfma_f32_16x16x32_bf16 v[40:43], v[232:235], v[162:165], v[40:43]
	v_mfma_f32_16x16x32_bf16 v[32:35], v[208:211], v[170:173], v[32:35]
	v_mfma_f32_16x16x32_bf16 v[24:27], v[232:235], v[170:173], v[24:27]
	v_mfma_f32_16x16x32_bf16 v[16:19], v[208:211], v[192:195], v[16:19]
	v_mfma_f32_16x16x32_bf16 v[8:11], v[232:235], v[192:195], v[8:11]
	v_mfma_f32_16x16x32_bf16 v[4:7], v[208:211], v[200:203], v[4:7]
	v_mfma_f32_16x16x32_bf16 v[0:3], v[232:235], v[200:203], v[0:3]
	s_add_i32 s72, s72, 2
	s_add_u32 s4, s4, 0x100
	s_addc_u32 s5, s5, 0
	s_add_u32 s70, s70, 0x100
	s_addc_u32 s71, s71, 0
	s_cmp_lt_u32 s72, 30
	s_barrier
	s_cbranch_scc1 .LBB0_505
	v_mov_b32_e32 v147, v142
	v_mov_b32_e32 v146, v143
	s_cmp_lt_i32 s16, 12
	s_mov_b64 s[4:5], -1
	s_cbranch_scc1 .LBB0_1052
	s_lshl_b32 s4, s18, 8
	s_add_i32 s4, s4, s80
	v_add_u32_e32 v149, s4, v147
	s_lshl_b32 s4, s16, 8
	s_add_i32 s4, s84, s4
	v_lshl_add_u32 v138, v146, 3, s4
	v_mad_i64_i32 v[140:141], s[4:5], v149, s97, 0
	v_cmp_gt_i32_e32 vcc, s34, v138
	s_and_saveexec_b64 s[10:11], vcc
	s_cbranch_execz .LBB0_541
	v_cmp_lt_i32_e64 s[8:9], 63, v138
	v_cmp_gt_u32_e64 s[4:5], s93, v138
	v_cmp_gt_u32_e64 s[6:7], s96, v138
	s_and_saveexec_b64 s[70:71], s[8:9]
	s_xor_b64 s[70:71], exec, s[70:71]
	s_cbranch_execz .LBB0_510
	v_mul_f32_e32 v139, 0xbfb8aa3b, v124
	v_exp_f32_e32 v139, v139
	s_nop 0
	v_add_f32_e32 v139, 1.0, v139
	v_rcp_f32_e32 v139, v139
	s_nop 0
	v_cndmask_b32_e64 v139, 0, v139, s[6:7]
	v_cndmask_b32_e64 v139, v139, v124, s[4:5]
	s_andn2_saveexec_b64 s[70:71], s[70:71]
	s_cbranch_execz .LBB0_512
	s_branch .LBB0_511

.LBB0_1114:
	s_add_i32 vcc_hi, s66, 2
	s_add_u32 s28, s64, 0x80
	s_addc_u32 s29, s65, 0
	s_add_i32 s88, 0, 0x10000
	v_add_u32_e32 v140, s88, v194
	ds_read_b128 v[128:131], v140
	ds_read_b128 v[132:135], v140 offset:1024
	ds_read_b128 v[136:139], v140 offset:2048
	ds_read_b128 v[140:143], v140 offset:3072
	s_cmp_eq_u32 s85, s66
	s_cselect_b32 s66, s4, s28
	s_cselect_b32 s67, s5, s29
	s_cselect_b32 s69, s7, vcc_lo
	s_cselect_b32 s68, s6, s91
	s_add_i32 m0, s70, 0xc000
	ds_read_b128 v[144:147], v195
	ds_read_b128 v[162:165], v195 offset:2048
	ds_read_b128 v[170:173], v195 offset:4096
	ds_read_b128 v[196:199], v195 offset:6144
	ds_read_b128 v[148:151], v195 offset:1024
	ds_read_b128 v[166:169], v195 offset:3072
	ds_read_b128 v[188:191], v195 offset:5120
	ds_read_b128 v[200:203], v195 offset:7168
	global_load_lds_dwordx4 v158, s[64:65]
	s_add_i32 m0, s70, 0xe000
	s_nop 0
	global_load_lds_dwordx4 v160, s[64:65]
	s_waitcnt lgkmcnt(8)
	s_barrier
	s_waitcnt lgkmcnt(7)
	v_mfma_f32_16x16x32_bf16 v[124:127], v[128:131], v[144:147], v[124:127]
	v_mfma_f32_16x16x32_bf16 v[120:123], v[136:139], v[144:147], v[120:123]
	s_waitcnt lgkmcnt(6)
	v_mfma_f32_16x16x32_bf16 v[108:111], v[128:131], v[162:165], v[108:111]
	v_mfma_f32_16x16x32_bf16 v[104:107], v[136:139], v[162:165], v[104:107]
	s_waitcnt lgkmcnt(5)
	v_mfma_f32_16x16x32_bf16 v[92:95], v[128:131], v[170:173], v[92:95]
	v_mfma_f32_16x16x32_bf16 v[88:91], v[136:139], v[170:173], v[88:91]
	s_waitcnt lgkmcnt(4)
	v_mfma_f32_16x16x32_bf16 v[76:79], v[128:131], v[196:199], v[76:79]
	v_mfma_f32_16x16x32_bf16 v[72:75], v[136:139], v[196:199], v[72:75]
	s_waitcnt lgkmcnt(3)
	v_mfma_f32_16x16x32_bf16 v[124:127], v[132:135], v[148:151], v[124:127]
	v_mfma_f32_16x16x32_bf16 v[120:123], v[140:143], v[148:151], v[120:123]
	s_waitcnt lgkmcnt(2)
	v_mfma_f32_16x16x32_bf16 v[108:111], v[132:135], v[166:169], v[108:111]
	v_mfma_f32_16x16x32_bf16 v[104:107], v[140:143], v[166:169], v[104:107]
	s_waitcnt lgkmcnt(1)
	v_mfma_f32_16x16x32_bf16 v[92:95], v[132:135], v[188:191], v[92:95]
	v_mfma_f32_16x16x32_bf16 v[88:91], v[140:143], v[188:191], v[88:91]
	s_waitcnt lgkmcnt(0)
	v_mfma_f32_16x16x32_bf16 v[76:79], v[132:135], v[200:203], v[76:79]
	v_mfma_f32_16x16x32_bf16 v[72:75], v[140:143], v[200:203], v[72:75]
	s_barrier
	s_add_i32 s28, 0, 0x14000
	v_add_u32_e32 v174, s28, v194
	s_add_i32 s29, s88, s47
	ds_read_b128 v[204:207], v174
	ds_read_b128 v[208:211], v174 offset:1024
	ds_read_b128 v[212:215], v174 offset:2048
	ds_read_b128 v[232:235], v174 offset:3072
	v_lshl_add_u64 v[174:175], s[68:69], 0, v[176:177]
	s_mov_b32 m0, s29
	v_lshl_add_u64 v[216:217], s[68:69], 0, v[156:157]
	global_load_lds_dwordx4 v176, s[68:69]
	s_add_i32 m0, s29, 0x2000
	s_nop 0
	global_load_lds_dwordx4 v156, s[68:69]
	s_barrier
	s_waitcnt lgkmcnt(3)
	v_mfma_f32_16x16x32_bf16 v[116:119], v[204:207], v[144:147], v[116:119]
	s_waitcnt lgkmcnt(1)
	v_mfma_f32_16x16x32_bf16 v[112:115], v[212:215], v[144:147], v[112:115]
	v_mfma_f32_16x16x32_bf16 v[100:103], v[204:207], v[162:165], v[100:103]
	v_mfma_f32_16x16x32_bf16 v[96:99], v[212:215], v[162:165], v[96:99]
	v_mfma_f32_16x16x32_bf16 v[84:87], v[204:207], v[170:173], v[84:87]
	v_mfma_f32_16x16x32_bf16 v[80:83], v[212:215], v[170:173], v[80:83]
	v_mfma_f32_16x16x32_bf16 v[68:71], v[204:207], v[196:199], v[68:71]
	v_mfma_f32_16x16x32_bf16 v[64:67], v[212:215], v[196:199], v[64:67]
	v_mfma_f32_16x16x32_bf16 v[116:119], v[208:211], v[148:151], v[116:119]
	s_waitcnt lgkmcnt(0)
	v_mfma_f32_16x16x32_bf16 v[112:115], v[232:235], v[148:151], v[112:115]
	v_mfma_f32_16x16x32_bf16 v[100:103], v[208:211], v[166:169], v[100:103]
	v_mfma_f32_16x16x32_bf16 v[96:99], v[232:235], v[166:169], v[96:99]
	v_mfma_f32_16x16x32_bf16 v[84:87], v[208:211], v[188:191], v[84:87]
	v_mfma_f32_16x16x32_bf16 v[80:83], v[232:235], v[188:191], v[80:83]
	v_mfma_f32_16x16x32_bf16 v[68:71], v[208:211], v[200:203], v[68:71]
	v_mfma_f32_16x16x32_bf16 v[64:67], v[232:235], v[200:203], v[64:67]
	s_mov_b32 m0, s70
	v_lshl_add_u64 v[236:237], s[66:67], 0, v[152:153]
	s_barrier
	ds_read_b128 v[144:147], v195 offset:16384
	ds_read_b128 v[162:165], v195 offset:18432
	ds_read_b128 v[170:173], v195 offset:20480
	ds_read_b128 v[196:199], v195 offset:22528
	ds_read_b128 v[148:151], v195 offset:17408
	ds_read_b128 v[166:169], v195 offset:19456
	ds_read_b128 v[188:191], v195 offset:21504
	ds_read_b128 v[200:203], v195 offset:23552
	global_load_lds_dwordx4 v152, s[66:67]
	v_lshl_add_u64 v[238:239], s[66:67], 0, v[154:155]
	s_mov_b32 m0, s71
	s_nop 0
	global_load_lds_dwordx4 v154, s[66:67]
	s_barrier
	s_waitcnt lgkmcnt(7)
	v_mfma_f32_16x16x32_bf16 v[60:63], v[128:131], v[144:147], v[60:63]
	v_mfma_f32_16x16x32_bf16 v[56:59], v[136:139], v[144:147], v[56:59]
	s_waitcnt lgkmcnt(6)
	v_mfma_f32_16x16x32_bf16 v[44:47], v[128:131], v[162:165], v[44:47]
	v_mfma_f32_16x16x32_bf16 v[40:43], v[136:139], v[162:165], v[40:43]
	s_waitcnt lgkmcnt(5)
	v_mfma_f32_16x16x32_bf16 v[28:31], v[128:131], v[170:173], v[28:31]
	v_mfma_f32_16x16x32_bf16 v[24:27], v[136:139], v[170:173], v[24:27]
	s_waitcnt lgkmcnt(4)
	v_mfma_f32_16x16x32_bf16 v[12:15], v[128:131], v[196:199], v[12:15]
	v_mfma_f32_16x16x32_bf16 v[8:11], v[136:139], v[196:199], v[8:11]
	s_waitcnt lgkmcnt(3)
	v_mfma_f32_16x16x32_bf16 v[60:63], v[132:135], v[148:151], v[60:63]
	v_mfma_f32_16x16x32_bf16 v[56:59], v[140:143], v[148:151], v[56:59]
	s_waitcnt lgkmcnt(2)
	v_mfma_f32_16x16x32_bf16 v[44:47], v[132:135], v[166:169], v[44:47]
	v_mfma_f32_16x16x32_bf16 v[40:43], v[140:143], v[166:169], v[40:43]
	s_waitcnt lgkmcnt(1)
	v_mfma_f32_16x16x32_bf16 v[28:31], v[132:135], v[188:191], v[28:31]
	v_mfma_f32_16x16x32_bf16 v[24:27], v[140:143], v[188:191], v[24:27]
	s_waitcnt lgkmcnt(0)
	v_mfma_f32_16x16x32_bf16 v[12:15], v[132:135], v[200:203], v[12:15]
	v_mfma_f32_16x16x32_bf16 v[8:11], v[140:143], v[200:203], v[8:11]
	s_barrier
	s_add_u32 s68, s68, s58
	s_addc_u32 s69, s69, 0
	s_add_i32 s28, s28, s47
	s_mov_b32 m0, s28
	s_nop 0
	global_load_lds_dwordx4 v176, s[68:69]
	s_add_i32 m0, s28, 0x2000
	s_nop 0
	global_load_lds_dwordx4 v156, s[68:69]
	s_waitcnt vmcnt(6)
	s_barrier
	v_mfma_f32_16x16x32_bf16 v[52:55], v[204:207], v[144:147], v[52:55]
	v_mfma_f32_16x16x32_bf16 v[48:51], v[212:215], v[144:147], v[48:51]
	v_mfma_f32_16x16x32_bf16 v[36:39], v[204:207], v[162:165], v[36:39]
	v_mfma_f32_16x16x32_bf16 v[32:35], v[212:215], v[162:165], v[32:35]
	v_mfma_f32_16x16x32_bf16 v[20:23], v[204:207], v[170:173], v[20:23]
	v_mfma_f32_16x16x32_bf16 v[16:19], v[212:215], v[170:173], v[16:19]
	v_mfma_f32_16x16x32_bf16 v[4:7], v[204:207], v[196:199], v[4:7]
	v_mfma_f32_16x16x32_bf16 v[0:3], v[212:215], v[196:199], v[0:3]
	v_mfma_f32_16x16x32_bf16 v[52:55], v[208:211], v[148:151], v[52:55]
	v_mfma_f32_16x16x32_bf16 v[48:51], v[232:235], v[148:151], v[48:51]
	v_mfma_f32_16x16x32_bf16 v[36:39], v[208:211], v[166:169], v[36:39]
	v_mfma_f32_16x16x32_bf16 v[32:35], v[232:235], v[166:169], v[32:35]
	v_mfma_f32_16x16x32_bf16 v[20:23], v[208:211], v[188:191], v[20:23]
	v_mfma_f32_16x16x32_bf16 v[16:19], v[232:235], v[188:191], v[16:19]
	v_mfma_f32_16x16x32_bf16 v[4:7], v[208:211], v[200:203], v[4:7]
	v_mfma_f32_16x16x32_bf16 v[0:3], v[232:235], v[200:203], v[0:3]
	s_add_i32 s28, 0, 0x18000
	v_add_u32_e32 v140, s28, v194
	s_barrier
	ds_read_b128 v[128:131], v140
	ds_read_b128 v[132:135], v140 offset:1024
	ds_read_b128 v[136:139], v140 offset:2048
	ds_read_b128 v[140:143], v140 offset:3072
	s_add_u32 s66, s66, s58
	s_addc_u32 s67, s67, 0
	s_mov_b32 m0, s72
	ds_read_b128 v[144:147], v195 offset:32768
	ds_read_b128 v[162:165], v195 offset:34816
	ds_read_b128 v[170:173], v195 offset:36864
	ds_read_b128 v[196:199], v195 offset:38912
	ds_read_b128 v[148:151], v195 offset:33792
	ds_read_b128 v[166:169], v195 offset:35840
	ds_read_b128 v[188:191], v195 offset:37888
	ds_read_b128 v[200:203], v195 offset:39936
	global_load_lds_dwordx4 v152, s[66:67]
	s_mov_b32 m0, s73
	s_nop 0
	global_load_lds_dwordx4 v154, s[66:67]
	s_waitcnt lgkmcnt(8)
	s_barrier
	s_waitcnt lgkmcnt(7)
	v_mfma_f32_16x16x32_bf16 v[124:127], v[128:131], v[144:147], v[124:127]
	v_mfma_f32_16x16x32_bf16 v[120:123], v[136:139], v[144:147], v[120:123]
	s_waitcnt lgkmcnt(6)
	v_mfma_f32_16x16x32_bf16 v[108:111], v[128:131], v[162:165], v[108:111]
	v_mfma_f32_16x16x32_bf16 v[104:107], v[136:139], v[162:165], v[104:107]
	s_waitcnt lgkmcnt(5)
	v_mfma_f32_16x16x32_bf16 v[92:95], v[128:131], v[170:173], v[92:95]
	v_mfma_f32_16x16x32_bf16 v[88:91], v[136:139], v[170:173], v[88:91]
	s_waitcnt lgkmcnt(4)
	v_mfma_f32_16x16x32_bf16 v[76:79], v[128:131], v[196:199], v[76:79]
	v_mfma_f32_16x16x32_bf16 v[72:75], v[136:139], v[196:199], v[72:75]
	s_waitcnt lgkmcnt(3)
	v_mfma_f32_16x16x32_bf16 v[124:127], v[132:135], v[148:151], v[124:127]
	v_mfma_f32_16x16x32_bf16 v[120:123], v[140:143], v[148:151], v[120:123]
	s_waitcnt lgkmcnt(2)
	v_mfma_f32_16x16x32_bf16 v[108:111], v[132:135], v[166:169], v[108:111]
	v_mfma_f32_16x16x32_bf16 v[104:107], v[140:143], v[166:169], v[104:107]
	s_waitcnt lgkmcnt(1)
	v_mfma_f32_16x16x32_bf16 v[92:95], v[132:135], v[188:191], v[92:95]
	v_mfma_f32_16x16x32_bf16 v[88:91], v[140:143], v[188:191], v[88:91]
	s_waitcnt lgkmcnt(0)
	v_mfma_f32_16x16x32_bf16 v[76:79], v[132:135], v[200:203], v[76:79]
	v_mfma_f32_16x16x32_bf16 v[72:75], v[140:143], v[200:203], v[72:75]
	s_barrier
	s_add_i32 s29, 0, 0x1c000
	s_add_i32 s28, s28, s47
	v_add_u32_e32 v232, s29, v194
	v_lshl_add_u64 v[174:175], v[174:175], 0, s[40:41]
	s_mov_b32 m0, s28
	ds_read_b128 v[204:207], v232
	ds_read_b128 v[208:211], v232 offset:1024
	ds_read_b128 v[212:215], v232 offset:2048
	ds_read_b128 v[232:235], v232 offset:3072
	global_load_lds_dwordx4 v[174:175], off
	v_lshl_add_u64 v[174:175], v[216:217], 0, s[40:41]
	s_add_i32 m0, s28, 0x2000
	s_nop 0
	global_load_lds_dwordx4 v[174:175], off
	s_barrier
	s_waitcnt lgkmcnt(3)
	v_mfma_f32_16x16x32_bf16 v[116:119], v[204:207], v[144:147], v[116:119]
	s_waitcnt lgkmcnt(1)
	v_mfma_f32_16x16x32_bf16 v[112:115], v[212:215], v[144:147], v[112:115]
	v_mfma_f32_16x16x32_bf16 v[100:103], v[204:207], v[162:165], v[100:103]
	v_mfma_f32_16x16x32_bf16 v[96:99], v[212:215], v[162:165], v[96:99]
	v_mfma_f32_16x16x32_bf16 v[84:87], v[204:207], v[170:173], v[84:87]
	v_mfma_f32_16x16x32_bf16 v[80:83], v[212:215], v[170:173], v[80:83]
	v_mfma_f32_16x16x32_bf16 v[68:71], v[204:207], v[196:199], v[68:71]
	v_mfma_f32_16x16x32_bf16 v[64:67], v[212:215], v[196:199], v[64:67]
	v_mfma_f32_16x16x32_bf16 v[116:119], v[208:211], v[148:151], v[116:119]
	s_waitcnt lgkmcnt(0)
	v_mfma_f32_16x16x32_bf16 v[112:115], v[232:235], v[148:151], v[112:115]
	v_mfma_f32_16x16x32_bf16 v[100:103], v[208:211], v[166:169], v[100:103]
	v_mfma_f32_16x16x32_bf16 v[96:99], v[232:235], v[166:169], v[96:99]
	v_mfma_f32_16x16x32_bf16 v[84:87], v[208:211], v[188:191], v[84:87]
	v_mfma_f32_16x16x32_bf16 v[80:83], v[232:235], v[188:191], v[80:83]
	v_mfma_f32_16x16x32_bf16 v[68:71], v[208:211], v[200:203], v[68:71]
	v_mfma_f32_16x16x32_bf16 v[64:67], v[232:235], v[200:203], v[64:67]
	s_mov_b32 m0, s74
	v_lshl_add_u64 v[174:175], v[236:237], 0, s[40:41]
	s_barrier
	ds_read_b128 v[144:147], v195 offset:49152
	ds_read_b128 v[162:165], v195 offset:51200
	ds_read_b128 v[170:173], v195 offset:53248
	ds_read_b128 v[196:199], v195 offset:55296
	ds_read_b128 v[148:151], v195 offset:50176
	ds_read_b128 v[166:169], v195 offset:52224
	ds_read_b128 v[188:191], v195 offset:54272
	ds_read_b128 v[200:203], v195 offset:56320
	global_load_lds_dwordx4 v[174:175], off
	v_lshl_add_u64 v[174:175], v[238:239], 0, s[40:41]
	s_mov_b32 m0, s75
	s_nop 0
	global_load_lds_dwordx4 v[174:175], off
	s_barrier
	s_waitcnt lgkmcnt(7)
	v_mfma_f32_16x16x32_bf16 v[60:63], v[128:131], v[144:147], v[60:63]
	v_mfma_f32_16x16x32_bf16 v[56:59], v[136:139], v[144:147], v[56:59]
	s_waitcnt lgkmcnt(6)
	v_mfma_f32_16x16x32_bf16 v[44:47], v[128:131], v[162:165], v[44:47]
	v_mfma_f32_16x16x32_bf16 v[40:43], v[136:139], v[162:165], v[40:43]
	s_waitcnt lgkmcnt(5)
	v_mfma_f32_16x16x32_bf16 v[28:31], v[128:131], v[170:173], v[28:31]
	v_mfma_f32_16x16x32_bf16 v[24:27], v[136:139], v[170:173], v[24:27]
	s_waitcnt lgkmcnt(4)
	v_mfma_f32_16x16x32_bf16 v[12:15], v[128:131], v[196:199], v[12:15]
	v_mfma_f32_16x16x32_bf16 v[8:11], v[136:139], v[196:199], v[8:11]
	s_waitcnt lgkmcnt(3)
	v_mfma_f32_16x16x32_bf16 v[60:63], v[132:135], v[148:151], v[60:63]
	v_mfma_f32_16x16x32_bf16 v[56:59], v[140:143], v[148:151], v[56:59]
	s_waitcnt lgkmcnt(2)
	v_mfma_f32_16x16x32_bf16 v[44:47], v[132:135], v[166:169], v[44:47]
	v_mfma_f32_16x16x32_bf16 v[40:43], v[140:143], v[166:169], v[40:43]
	s_waitcnt lgkmcnt(1)
	v_mfma_f32_16x16x32_bf16 v[28:31], v[132:135], v[188:191], v[28:31]
	v_mfma_f32_16x16x32_bf16 v[24:27], v[140:143], v[188:191], v[24:27]
	s_waitcnt lgkmcnt(0)
	v_mfma_f32_16x16x32_bf16 v[12:15], v[132:135], v[200:203], v[12:15]
	v_mfma_f32_16x16x32_bf16 v[8:11], v[140:143], v[200:203], v[8:11]
	s_barrier
	s_add_i32 s28, s29, s47
	s_add_u32 s98, s68, 0x80
	s_addc_u32 s99, s69, 0
	s_mov_b32 m0, s28
	s_nop 0
	global_load_lds_dwordx4 v176, s[98:99]
	s_add_i32 m0, s28, 0x2000
	s_nop 0
	global_load_lds_dwordx4 v156, s[98:99]
	s_waitcnt vmcnt(6)
	s_barrier
	v_mfma_f32_16x16x32_bf16 v[52:55], v[204:207], v[144:147], v[52:55]
	v_mfma_f32_16x16x32_bf16 v[48:51], v[212:215], v[144:147], v[48:51]
	v_mfma_f32_16x16x32_bf16 v[36:39], v[204:207], v[162:165], v[36:39]
	v_mfma_f32_16x16x32_bf16 v[32:35], v[212:215], v[162:165], v[32:35]
	v_mfma_f32_16x16x32_bf16 v[20:23], v[204:207], v[170:173], v[20:23]
	v_mfma_f32_16x16x32_bf16 v[16:19], v[212:215], v[170:173], v[16:19]
	v_mfma_f32_16x16x32_bf16 v[4:7], v[204:207], v[196:199], v[4:7]
	v_mfma_f32_16x16x32_bf16 v[0:3], v[212:215], v[196:199], v[0:3]
	v_mfma_f32_16x16x32_bf16 v[52:55], v[208:211], v[148:151], v[52:55]
	v_mfma_f32_16x16x32_bf16 v[48:51], v[232:235], v[148:151], v[48:51]
	v_mfma_f32_16x16x32_bf16 v[36:39], v[208:211], v[166:169], v[36:39]
	v_mfma_f32_16x16x32_bf16 v[32:35], v[232:235], v[166:169], v[32:35]
	v_mfma_f32_16x16x32_bf16 v[20:23], v[208:211], v[188:191], v[20:23]
	v_mfma_f32_16x16x32_bf16 v[16:19], v[232:235], v[188:191], v[16:19]
	v_mfma_f32_16x16x32_bf16 v[4:7], v[208:211], v[200:203], v[4:7]
	v_mfma_f32_16x16x32_bf16 v[0:3], v[232:235], v[200:203], v[0:3]
	s_add_u32 s64, s64, 0x100
	s_addc_u32 s65, s65, 0
	s_add_u32 s91, s91, 0x100
	s_addc_u32 vcc_lo, vcc_lo, 0
	s_cmp_lt_i32 vcc_hi, s76
	s_mov_b32 s66, vcc_hi
	s_barrier
	s_cbranch_scc1 .LBB0_1114
	s_lshl_b32 s28, s84, 8
	v_mov_b32_e32 v128, v193
	v_mov_b32_e32 v129, v192
	s_add_i32 s28, s28, s78
	s_lshl_b32 s64, s24, 2
	v_add_u32_e32 v166, s28, v129
	s_lshl_b32 s28, s24, 8
	s_or_b32 s28, s28, s79
	v_lshl_add_u32 v162, v128, 3, s28
	v_ashrrev_i32_e32 v163, 31, v162
	v_lshlrev_b64 v[204:205], 1, v[162:163]
	v_ashrrev_i32_e32 v167, 31, v166
	v_lshl_add_u64 v[164:165], s[12:13], 0, v[204:205]
	v_lshlrev_b64 v[206:207], 11, v[166:167]
	v_cmp_eq_u32_e32 vcc, 0, v128
	v_lshl_add_u64 v[128:129], v[164:165], 0, v[206:207]
	global_load_dwordx4 v[196:199], v[128:129], off
	global_load_dwordx4 v[200:203], v[128:129], off offset:256
	v_add_u32_e32 v188, 16, v166
	v_ashrrev_i32_e32 v189, 31, v188
	v_add_u32_e32 v172, 32, v166
	v_lshlrev_b64 v[190:191], 11, v[188:189]
	v_ashrrev_i32_e32 v173, 31, v172
	v_add_u32_e32 v168, 48, v166
	v_lshl_add_u64 v[128:129], v[164:165], 0, v[190:191]
	v_lshlrev_b64 v[174:175], 11, v[172:173]
	v_ashrrev_i32_e32 v169, 31, v168
	global_load_dwordx4 v[148:151], v[128:129], off
	global_load_dwordx4 v[144:147], v[128:129], off offset:256
	v_lshl_add_u64 v[128:129], v[164:165], 0, v[174:175]
	v_lshlrev_b64 v[170:171], 11, v[168:169]
	global_load_dwordx4 v[140:143], v[128:129], off
	global_load_dwordx4 v[136:139], v[128:129], off offset:256
	v_lshl_add_u64 v[128:129], v[164:165], 0, v[170:171]
	global_load_dwordx4 v[132:135], v[128:129], off
	s_nop 0
	global_load_dwordx4 v[128:131], v[128:129], off offset:256
	v_lshl_add_u64 v[206:207], s[12:13], 0, v[206:207]
	v_lshl_add_u64 v[204:205], v[206:207], 0, v[204:205]
	s_ashr_i32 s65, s64, 31
	s_waitcnt vmcnt(0)
	v_lshlrev_b32_e32 v208, 16, v196
	v_and_b32_e32 v209, 0xffff0000, v196
	v_lshlrev_b32_e32 v196, 16, v197
	v_and_b32_e32 v197, 0xffff0000, v197
	v_lshlrev_b32_e32 v210, 16, v198
	v_and_b32_e32 v211, 0xffff0000, v198
	v_lshlrev_b32_e32 v198, 16, v199
	v_and_b32_e32 v199, 0xffff0000, v199
	v_pk_fma_f32 v[126:127], s[62:63], v[126:127], v[196:197]
	v_pk_fma_f32 v[124:125], s[10:11], v[124:125], v[208:209]
	v_pk_fma_f32 v[196:197], s[62:63], v[122:123], v[198:199]
	v_pk_fma_f32 v[198:199], s[10:11], v[120:121], v[210:211]
	v_cvt_pk_bf16_f32 v120, v124, v125
	v_cvt_pk_bf16_f32 v121, v126, v127
	s_nop 0
	v_cvt_pk_bf16_f32 v122, v198, v199
	v_cvt_pk_bf16_f32 v123, v196, v197
	global_store_dwordx4 v[204:205], v[120:123], off
	s_nop 1
	v_pk_mul_f32 v[120:121], v[198:199], v[198:199]
	v_pk_mul_f32 v[122:123], v[196:197], v[196:197]
	v_pk_fma_f32 v[120:121], v[124:125], v[124:125], v[120:121]
	v_pk_fma_f32 v[122:123], v[126:127], v[126:127], v[122:123]
	v_add_f32_e32 v120, v120, v121
	v_add_f32_e32 v121, v122, v123
	v_add_f32_e32 v196, v120, v121
	v_lshlrev_b32_e32 v120, 16, v200
	v_and_b32_e32 v121, 0xffff0000, v200
	v_lshlrev_b32_e32 v122, 16, v201
	v_and_b32_e32 v123, 0xffff0000, v201
	v_lshlrev_b32_e32 v124, 16, v202
	v_and_b32_e32 v125, 0xffff0000, v202
	v_lshlrev_b32_e32 v126, 16, v203
	v_and_b32_e32 v127, 0xffff0000, v203
	v_pk_fma_f32 v[118:119], s[62:63], v[118:119], v[122:123]
	v_pk_fma_f32 v[116:117], s[10:11], v[116:117], v[120:121]
	v_pk_fma_f32 v[120:121], s[62:63], v[114:115], v[126:127]
	v_pk_fma_f32 v[122:123], s[10:11], v[112:113], v[124:125]
	v_cvt_pk_bf16_f32 v112, v116, v117
	v_cvt_pk_bf16_f32 v113, v118, v119
	s_nop 0
	v_cvt_pk_bf16_f32 v114, v122, v123
	v_cvt_pk_bf16_f32 v115, v120, v121
	global_store_dwordx4 v[204:205], v[112:115], off offset:256
	s_nop 1
	v_pk_mul_f32 v[112:113], v[122:123], v[122:123]
	v_pk_mul_f32 v[114:115], v[120:121], v[120:121]
	v_pk_fma_f32 v[112:113], v[116:117], v[116:117], v[112:113]
	v_pk_fma_f32 v[114:115], v[118:119], v[118:119], v[114:115]
	v_add_f32_e32 v112, v112, v113
	v_add_f32_e32 v113, v114, v115
	v_add_f32_e32 v112, v112, v113
	v_add_f32_e32 v112, v196, v112
	ds_bpermute_b32 v113, v219, v112
	s_waitcnt lgkmcnt(0)
	v_add_f32_e32 v112, v112, v113
	ds_bpermute_b32 v113, v218, v112
	s_and_saveexec_b64 s[66:67], vcc
	s_cbranch_execz .LBB0_1117
	v_lshlrev_b64 v[114:115], 6, v[166:167]
	v_lshl_add_u64 v[114:115], s[8:9], 0, v[114:115]
	v_lshl_add_u64 v[114:115], s[64:65], 2, v[114:115]
	s_lshl_b32 s24, s77, 2
	v_lshl_add_u64 v[114:115], v[114:115], 0, s[24:25]
	s_waitcnt lgkmcnt(0)
	v_add_f32_e32 v112, v112, v113
	global_store_dword v[114:115], v112, off

.LBB0_1282:
	s_add_i32 s81, s60, 2
	s_add_u32 s28, s58, 0x80
	s_addc_u32 s29, s59, 0
	s_add_i32 s82, 0, 0x10000
	v_add_u32_e32 v140, s82, v195
	ds_read_b128 v[128:131], v140
	ds_read_b128 v[132:135], v140 offset:1024
	ds_read_b128 v[136:139], v140 offset:2048
	ds_read_b128 v[140:143], v140 offset:3072
	s_cmp_eq_u32 s5, s60
	s_cselect_b32 s60, s56, s28
	s_cselect_b32 s61, s57, s29
	s_cselect_b32 s63, s3, s80
	s_cselect_b32 s62, s2, s21
	s_add_i32 m0, s66, 0xc000
	ds_read_b128 v[144:147], v196
	ds_read_b128 v[162:165], v196 offset:2048
	ds_read_b128 v[170:173], v196 offset:4096
	ds_read_b128 v[198:201], v196 offset:6144
	ds_read_b128 v[148:151], v196 offset:1024
	ds_read_b128 v[166:169], v196 offset:3072
	ds_read_b128 v[188:191], v196 offset:5120
	ds_read_b128 v[202:205], v196 offset:7168
	global_load_lds_dwordx4 v158, s[58:59]
	s_add_i32 m0, s66, 0xe000
	s_nop 0
	global_load_lds_dwordx4 v160, s[58:59]
	s_waitcnt lgkmcnt(8)
	s_barrier
	s_waitcnt lgkmcnt(7)
	v_mfma_f32_16x16x32_bf16 v[124:127], v[128:131], v[144:147], v[124:127]
	v_mfma_f32_16x16x32_bf16 v[120:123], v[136:139], v[144:147], v[120:123]
	s_waitcnt lgkmcnt(6)
	v_mfma_f32_16x16x32_bf16 v[108:111], v[128:131], v[162:165], v[108:111]
	v_mfma_f32_16x16x32_bf16 v[104:107], v[136:139], v[162:165], v[104:107]
	s_waitcnt lgkmcnt(5)
	v_mfma_f32_16x16x32_bf16 v[92:95], v[128:131], v[170:173], v[92:95]
	v_mfma_f32_16x16x32_bf16 v[88:91], v[136:139], v[170:173], v[88:91]
	s_waitcnt lgkmcnt(4)
	v_mfma_f32_16x16x32_bf16 v[76:79], v[128:131], v[198:201], v[76:79]
	v_mfma_f32_16x16x32_bf16 v[72:75], v[136:139], v[198:201], v[72:75]
	s_waitcnt lgkmcnt(3)
	v_mfma_f32_16x16x32_bf16 v[124:127], v[132:135], v[148:151], v[124:127]
	v_mfma_f32_16x16x32_bf16 v[120:123], v[140:143], v[148:151], v[120:123]
	s_waitcnt lgkmcnt(2)
	v_mfma_f32_16x16x32_bf16 v[108:111], v[132:135], v[166:169], v[108:111]
	v_mfma_f32_16x16x32_bf16 v[104:107], v[140:143], v[166:169], v[104:107]
	s_waitcnt lgkmcnt(1)
	v_mfma_f32_16x16x32_bf16 v[92:95], v[132:135], v[188:191], v[92:95]
	v_mfma_f32_16x16x32_bf16 v[88:91], v[140:143], v[188:191], v[88:91]
	s_waitcnt lgkmcnt(0)
	v_mfma_f32_16x16x32_bf16 v[76:79], v[132:135], v[202:205], v[76:79]
	v_mfma_f32_16x16x32_bf16 v[72:75], v[140:143], v[202:205], v[72:75]
	s_barrier
	s_add_i32 s28, 0, 0x14000
	v_add_u32_e32 v174, s28, v195
	s_add_i32 s29, s82, s65
	ds_read_b128 v[206:209], v174
	ds_read_b128 v[210:213], v174 offset:1024
	ds_read_b128 v[214:217], v174 offset:2048
	ds_read_b128 v[232:235], v174 offset:3072
	v_lshl_add_u64 v[174:175], s[62:63], 0, v[176:177]
	s_mov_b32 m0, s29
	v_lshl_add_u64 v[236:237], s[62:63], 0, v[156:157]
	global_load_lds_dwordx4 v176, s[62:63]
	s_add_i32 m0, s29, 0x2000
	s_nop 0
	global_load_lds_dwordx4 v156, s[62:63]
	s_barrier
	s_waitcnt lgkmcnt(3)
	v_mfma_f32_16x16x32_bf16 v[116:119], v[206:209], v[144:147], v[116:119]
	s_waitcnt lgkmcnt(1)
	v_mfma_f32_16x16x32_bf16 v[112:115], v[214:217], v[144:147], v[112:115]
	v_mfma_f32_16x16x32_bf16 v[100:103], v[206:209], v[162:165], v[100:103]
	v_mfma_f32_16x16x32_bf16 v[96:99], v[214:217], v[162:165], v[96:99]
	v_mfma_f32_16x16x32_bf16 v[84:87], v[206:209], v[170:173], v[84:87]
	v_mfma_f32_16x16x32_bf16 v[80:83], v[214:217], v[170:173], v[80:83]
	v_mfma_f32_16x16x32_bf16 v[68:71], v[206:209], v[198:201], v[68:71]
	v_mfma_f32_16x16x32_bf16 v[64:67], v[214:217], v[198:201], v[64:67]
	v_mfma_f32_16x16x32_bf16 v[116:119], v[210:213], v[148:151], v[116:119]
	s_waitcnt lgkmcnt(0)
	v_mfma_f32_16x16x32_bf16 v[112:115], v[232:235], v[148:151], v[112:115]
	v_mfma_f32_16x16x32_bf16 v[100:103], v[210:213], v[166:169], v[100:103]
	v_mfma_f32_16x16x32_bf16 v[96:99], v[232:235], v[166:169], v[96:99]
	v_mfma_f32_16x16x32_bf16 v[84:87], v[210:213], v[188:191], v[84:87]
	v_mfma_f32_16x16x32_bf16 v[80:83], v[232:235], v[188:191], v[80:83]
	v_mfma_f32_16x16x32_bf16 v[68:71], v[210:213], v[202:205], v[68:71]
	v_mfma_f32_16x16x32_bf16 v[64:67], v[232:235], v[202:205], v[64:67]
	s_mov_b32 m0, s66
	v_lshl_add_u64 v[238:239], s[60:61], 0, v[152:153]
	s_barrier
	ds_read_b128 v[144:147], v196 offset:16384
	ds_read_b128 v[162:165], v196 offset:18432
	ds_read_b128 v[170:173], v196 offset:20480
	ds_read_b128 v[198:201], v196 offset:22528
	ds_read_b128 v[148:151], v196 offset:17408
	ds_read_b128 v[166:169], v196 offset:19456
	ds_read_b128 v[188:191], v196 offset:21504
	ds_read_b128 v[202:205], v196 offset:23552
	global_load_lds_dwordx4 v152, s[60:61]
	v_lshl_add_u64 v[240:241], s[60:61], 0, v[154:155]
	s_mov_b32 m0, s67
	s_nop 0
	global_load_lds_dwordx4 v154, s[60:61]
	s_barrier
	s_waitcnt lgkmcnt(7)
	v_mfma_f32_16x16x32_bf16 v[60:63], v[128:131], v[144:147], v[60:63]
	v_mfma_f32_16x16x32_bf16 v[56:59], v[136:139], v[144:147], v[56:59]
	s_waitcnt lgkmcnt(6)
	v_mfma_f32_16x16x32_bf16 v[44:47], v[128:131], v[162:165], v[44:47]
	v_mfma_f32_16x16x32_bf16 v[40:43], v[136:139], v[162:165], v[40:43]
	s_waitcnt lgkmcnt(5)
	v_mfma_f32_16x16x32_bf16 v[28:31], v[128:131], v[170:173], v[28:31]
	v_mfma_f32_16x16x32_bf16 v[24:27], v[136:139], v[170:173], v[24:27]
	s_waitcnt lgkmcnt(4)
	v_mfma_f32_16x16x32_bf16 v[12:15], v[128:131], v[198:201], v[12:15]
	v_mfma_f32_16x16x32_bf16 v[8:11], v[136:139], v[198:201], v[8:11]
	s_waitcnt lgkmcnt(3)
	v_mfma_f32_16x16x32_bf16 v[60:63], v[132:135], v[148:151], v[60:63]
	v_mfma_f32_16x16x32_bf16 v[56:59], v[140:143], v[148:151], v[56:59]
	s_waitcnt lgkmcnt(2)
	v_mfma_f32_16x16x32_bf16 v[44:47], v[132:135], v[166:169], v[44:47]
	v_mfma_f32_16x16x32_bf16 v[40:43], v[140:143], v[166:169], v[40:43]
	s_waitcnt lgkmcnt(1)
	v_mfma_f32_16x16x32_bf16 v[28:31], v[132:135], v[188:191], v[28:31]
	v_mfma_f32_16x16x32_bf16 v[24:27], v[140:143], v[188:191], v[24:27]
	s_waitcnt lgkmcnt(0)
	v_mfma_f32_16x16x32_bf16 v[12:15], v[132:135], v[202:205], v[12:15]
	v_mfma_f32_16x16x32_bf16 v[8:11], v[140:143], v[202:205], v[8:11]
	s_barrier
	s_add_u32 s62, s62, s4
	s_addc_u32 s63, s63, 0
	s_add_i32 s28, s28, s65
	s_mov_b32 m0, s28
	s_nop 0
	global_load_lds_dwordx4 v176, s[62:63]
	s_add_i32 m0, s28, 0x2000
	s_nop 0
	global_load_lds_dwordx4 v156, s[62:63]
	s_waitcnt vmcnt(6)
	s_barrier
	v_mfma_f32_16x16x32_bf16 v[52:55], v[206:209], v[144:147], v[52:55]
	v_mfma_f32_16x16x32_bf16 v[48:51], v[214:217], v[144:147], v[48:51]
	v_mfma_f32_16x16x32_bf16 v[36:39], v[206:209], v[162:165], v[36:39]
	v_mfma_f32_16x16x32_bf16 v[32:35], v[214:217], v[162:165], v[32:35]
	v_mfma_f32_16x16x32_bf16 v[20:23], v[206:209], v[170:173], v[20:23]
	v_mfma_f32_16x16x32_bf16 v[16:19], v[214:217], v[170:173], v[16:19]
	v_mfma_f32_16x16x32_bf16 v[4:7], v[206:209], v[198:201], v[4:7]
	v_mfma_f32_16x16x32_bf16 v[0:3], v[214:217], v[198:201], v[0:3]
	v_mfma_f32_16x16x32_bf16 v[52:55], v[210:213], v[148:151], v[52:55]
	v_mfma_f32_16x16x32_bf16 v[48:51], v[232:235], v[148:151], v[48:51]
	v_mfma_f32_16x16x32_bf16 v[36:39], v[210:213], v[166:169], v[36:39]
	v_mfma_f32_16x16x32_bf16 v[32:35], v[232:235], v[166:169], v[32:35]
	v_mfma_f32_16x16x32_bf16 v[20:23], v[210:213], v[188:191], v[20:23]
	v_mfma_f32_16x16x32_bf16 v[16:19], v[232:235], v[188:191], v[16:19]
	v_mfma_f32_16x16x32_bf16 v[4:7], v[210:213], v[202:205], v[4:7]
	v_mfma_f32_16x16x32_bf16 v[0:3], v[232:235], v[202:205], v[0:3]
	s_add_i32 s28, 0, 0x18000
	v_add_u32_e32 v140, s28, v195
	s_barrier
	ds_read_b128 v[128:131], v140
	ds_read_b128 v[132:135], v140 offset:1024
	ds_read_b128 v[136:139], v140 offset:2048
	ds_read_b128 v[140:143], v140 offset:3072
	s_add_u32 s60, s60, s4
	s_addc_u32 s61, s61, 0
	s_mov_b32 m0, s68
	ds_read_b128 v[144:147], v196 offset:32768
	ds_read_b128 v[162:165], v196 offset:34816
	ds_read_b128 v[170:173], v196 offset:36864
	ds_read_b128 v[198:201], v196 offset:38912
	ds_read_b128 v[148:151], v196 offset:33792
	ds_read_b128 v[166:169], v196 offset:35840
	ds_read_b128 v[188:191], v196 offset:37888
	ds_read_b128 v[202:205], v196 offset:39936
	global_load_lds_dwordx4 v152, s[60:61]
	s_mov_b32 m0, s69
	s_nop 0
	global_load_lds_dwordx4 v154, s[60:61]
	s_waitcnt lgkmcnt(8)
	s_barrier
	s_waitcnt lgkmcnt(7)
	v_mfma_f32_16x16x32_bf16 v[124:127], v[128:131], v[144:147], v[124:127]
	v_mfma_f32_16x16x32_bf16 v[120:123], v[136:139], v[144:147], v[120:123]
	s_waitcnt lgkmcnt(6)
	v_mfma_f32_16x16x32_bf16 v[108:111], v[128:131], v[162:165], v[108:111]
	v_mfma_f32_16x16x32_bf16 v[104:107], v[136:139], v[162:165], v[104:107]
	s_waitcnt lgkmcnt(5)
	v_mfma_f32_16x16x32_bf16 v[92:95], v[128:131], v[170:173], v[92:95]
	v_mfma_f32_16x16x32_bf16 v[88:91], v[136:139], v[170:173], v[88:91]
	s_waitcnt lgkmcnt(4)
	v_mfma_f32_16x16x32_bf16 v[76:79], v[128:131], v[198:201], v[76:79]
	v_mfma_f32_16x16x32_bf16 v[72:75], v[136:139], v[198:201], v[72:75]
	s_waitcnt lgkmcnt(3)
	v_mfma_f32_16x16x32_bf16 v[124:127], v[132:135], v[148:151], v[124:127]
	v_mfma_f32_16x16x32_bf16 v[120:123], v[140:143], v[148:151], v[120:123]
	s_waitcnt lgkmcnt(2)
	v_mfma_f32_16x16x32_bf16 v[108:111], v[132:135], v[166:169], v[108:111]
	v_mfma_f32_16x16x32_bf16 v[104:107], v[140:143], v[166:169], v[104:107]
	s_waitcnt lgkmcnt(1)
	v_mfma_f32_16x16x32_bf16 v[92:95], v[132:135], v[188:191], v[92:95]
	v_mfma_f32_16x16x32_bf16 v[88:91], v[140:143], v[188:191], v[88:91]
	s_waitcnt lgkmcnt(0)
	v_mfma_f32_16x16x32_bf16 v[76:79], v[132:135], v[202:205], v[76:79]
	v_mfma_f32_16x16x32_bf16 v[72:75], v[140:143], v[202:205], v[72:75]
	s_barrier
	s_add_i32 s29, 0, 0x1c000
	s_add_i32 s28, s28, s65
	v_add_u32_e32 v197, s29, v195
	v_lshl_add_u64 v[174:175], v[174:175], 0, s[40:41]
	s_mov_b32 m0, s28
	ds_read_b128 v[206:209], v197
	ds_read_b128 v[210:213], v197 offset:1024
	ds_read_b128 v[214:217], v197 offset:2048
	ds_read_b128 v[232:235], v197 offset:3072
	global_load_lds_dwordx4 v[174:175], off
	v_lshl_add_u64 v[174:175], v[236:237], 0, s[40:41]
	s_add_i32 m0, s28, 0x2000
	s_nop 0
	global_load_lds_dwordx4 v[174:175], off
	s_barrier
	s_waitcnt lgkmcnt(3)
	v_mfma_f32_16x16x32_bf16 v[116:119], v[206:209], v[144:147], v[116:119]
	s_waitcnt lgkmcnt(1)
	v_mfma_f32_16x16x32_bf16 v[112:115], v[214:217], v[144:147], v[112:115]
	v_mfma_f32_16x16x32_bf16 v[100:103], v[206:209], v[162:165], v[100:103]
	v_mfma_f32_16x16x32_bf16 v[96:99], v[214:217], v[162:165], v[96:99]
	v_mfma_f32_16x16x32_bf16 v[84:87], v[206:209], v[170:173], v[84:87]
	v_mfma_f32_16x16x32_bf16 v[80:83], v[214:217], v[170:173], v[80:83]
	v_mfma_f32_16x16x32_bf16 v[68:71], v[206:209], v[198:201], v[68:71]
	v_mfma_f32_16x16x32_bf16 v[64:67], v[214:217], v[198:201], v[64:67]
	v_mfma_f32_16x16x32_bf16 v[116:119], v[210:213], v[148:151], v[116:119]
	s_waitcnt lgkmcnt(0)
	v_mfma_f32_16x16x32_bf16 v[112:115], v[232:235], v[148:151], v[112:115]
	v_mfma_f32_16x16x32_bf16 v[100:103], v[210:213], v[166:169], v[100:103]
	v_mfma_f32_16x16x32_bf16 v[96:99], v[232:235], v[166:169], v[96:99]
	v_mfma_f32_16x16x32_bf16 v[84:87], v[210:213], v[188:191], v[84:87]
	v_mfma_f32_16x16x32_bf16 v[80:83], v[232:235], v[188:191], v[80:83]
	v_mfma_f32_16x16x32_bf16 v[68:71], v[210:213], v[202:205], v[68:71]
	v_mfma_f32_16x16x32_bf16 v[64:67], v[232:235], v[202:205], v[64:67]
	s_mov_b32 m0, s71
	v_lshl_add_u64 v[174:175], v[238:239], 0, s[40:41]
	s_barrier
	ds_read_b128 v[144:147], v196 offset:49152
	ds_read_b128 v[162:165], v196 offset:51200
	ds_read_b128 v[170:173], v196 offset:53248
	ds_read_b128 v[198:201], v196 offset:55296
	ds_read_b128 v[148:151], v196 offset:50176
	ds_read_b128 v[166:169], v196 offset:52224
	ds_read_b128 v[188:191], v196 offset:54272
	ds_read_b128 v[202:205], v196 offset:56320
	global_load_lds_dwordx4 v[174:175], off
	v_lshl_add_u64 v[174:175], v[240:241], 0, s[40:41]
	s_mov_b32 m0, s72
	s_nop 0
	global_load_lds_dwordx4 v[174:175], off
	s_barrier
	s_waitcnt lgkmcnt(7)
	v_mfma_f32_16x16x32_bf16 v[60:63], v[128:131], v[144:147], v[60:63]
	v_mfma_f32_16x16x32_bf16 v[56:59], v[136:139], v[144:147], v[56:59]
	s_waitcnt lgkmcnt(6)
	v_mfma_f32_16x16x32_bf16 v[44:47], v[128:131], v[162:165], v[44:47]
	v_mfma_f32_16x16x32_bf16 v[40:43], v[136:139], v[162:165], v[40:43]
	s_waitcnt lgkmcnt(5)
	v_mfma_f32_16x16x32_bf16 v[28:31], v[128:131], v[170:173], v[28:31]
	v_mfma_f32_16x16x32_bf16 v[24:27], v[136:139], v[170:173], v[24:27]
	s_waitcnt lgkmcnt(4)
	v_mfma_f32_16x16x32_bf16 v[12:15], v[128:131], v[198:201], v[12:15]
	v_mfma_f32_16x16x32_bf16 v[8:11], v[136:139], v[198:201], v[8:11]
	s_waitcnt lgkmcnt(3)
	v_mfma_f32_16x16x32_bf16 v[60:63], v[132:135], v[148:151], v[60:63]
	v_mfma_f32_16x16x32_bf16 v[56:59], v[140:143], v[148:151], v[56:59]
	s_waitcnt lgkmcnt(2)
	v_mfma_f32_16x16x32_bf16 v[44:47], v[132:135], v[166:169], v[44:47]
	v_mfma_f32_16x16x32_bf16 v[40:43], v[140:143], v[166:169], v[40:43]
	s_waitcnt lgkmcnt(1)
	v_mfma_f32_16x16x32_bf16 v[28:31], v[132:135], v[188:191], v[28:31]
	v_mfma_f32_16x16x32_bf16 v[24:27], v[140:143], v[188:191], v[24:27]
	s_waitcnt lgkmcnt(0)
	v_mfma_f32_16x16x32_bf16 v[12:15], v[132:135], v[202:205], v[12:15]
	v_mfma_f32_16x16x32_bf16 v[8:11], v[140:143], v[202:205], v[8:11]
	s_barrier
	s_add_i32 s28, s29, s65
	s_add_u32 s98, s62, 0x80
	s_addc_u32 s99, s63, 0
	s_mov_b32 m0, s28
	s_nop 0
	global_load_lds_dwordx4 v176, s[98:99]
	s_add_i32 m0, s28, 0x2000
	s_nop 0
	global_load_lds_dwordx4 v156, s[98:99]
	s_waitcnt vmcnt(6)
	s_barrier
	v_mfma_f32_16x16x32_bf16 v[52:55], v[206:209], v[144:147], v[52:55]
	v_mfma_f32_16x16x32_bf16 v[48:51], v[214:217], v[144:147], v[48:51]
	v_mfma_f32_16x16x32_bf16 v[36:39], v[206:209], v[162:165], v[36:39]
	v_mfma_f32_16x16x32_bf16 v[32:35], v[214:217], v[162:165], v[32:35]
	v_mfma_f32_16x16x32_bf16 v[20:23], v[206:209], v[170:173], v[20:23]
	v_mfma_f32_16x16x32_bf16 v[16:19], v[214:217], v[170:173], v[16:19]
	v_mfma_f32_16x16x32_bf16 v[4:7], v[206:209], v[198:201], v[4:7]
	v_mfma_f32_16x16x32_bf16 v[0:3], v[214:217], v[198:201], v[0:3]
	v_mfma_f32_16x16x32_bf16 v[52:55], v[210:213], v[148:151], v[52:55]
	v_mfma_f32_16x16x32_bf16 v[48:51], v[232:235], v[148:151], v[48:51]
	v_mfma_f32_16x16x32_bf16 v[36:39], v[210:213], v[166:169], v[36:39]
	v_mfma_f32_16x16x32_bf16 v[32:35], v[232:235], v[166:169], v[32:35]
	v_mfma_f32_16x16x32_bf16 v[20:23], v[210:213], v[188:191], v[20:23]
	v_mfma_f32_16x16x32_bf16 v[16:19], v[232:235], v[188:191], v[16:19]
	v_mfma_f32_16x16x32_bf16 v[4:7], v[210:213], v[202:205], v[4:7]
	v_mfma_f32_16x16x32_bf16 v[0:3], v[232:235], v[202:205], v[0:3]
	s_add_u32 s58, s58, 0x100
	s_addc_u32 s59, s59, 0
	s_add_u32 s21, s21, 0x100
	s_addc_u32 s80, s80, 0
	s_cmp_ge_i32 s81, s79
	s_mov_b32 s60, s81
	s_barrier
	s_cbranch_scc0 .LBB0_1282
	s_cmp_gt_i32 s24, -1
	s_mov_b64 s[58:59], -1
	s_cbranch_scc0 .LBB0_1285
	s_lshl_b64 s[58:59], s[24:25], 17
	v_mov_b32_e32 v128, v231
	s_add_u32 s58, s37, s58
	s_addc_u32 s59, s46, s59
	v_ashrrev_i32_e32 v129, 31, v128
	v_lshl_add_u64 v[128:129], v[128:129], 4, s[58:59]
	v_add_co_u32_e32 v134, vcc, s36, v128
	v_cvt_pk_bf16_f32 v130, v124, v125
	v_cvt_pk_bf16_f32 v131, v126, v127
	v_cvt_pk_bf16_f32 v132, v120, v121
	v_cvt_pk_bf16_f32 v133, v122, v123
	s_nop 1
	v_addc_co_u32_e32 v135, vcc, 0, v129, vcc
	s_movk_i32 s5, 0x4000
	global_store_dwordx4 v[128:129], v[130:133], off
	s_mov_b64 s[58:59], 0
	s_nop 0
	v_cvt_pk_bf16_f32 v130, v108, v109
	v_cvt_pk_bf16_f32 v131, v110, v111
	v_cvt_pk_bf16_f32 v132, v104, v105
	v_cvt_pk_bf16_f32 v133, v106, v107
	global_store_dwordx4 v[134:135], v[130:133], off
	v_add_co_u32_e32 v134, vcc, s5, v128
	s_movk_i32 s5, 0x6000
	s_nop 0
	v_addc_co_u32_e32 v135, vcc, 0, v129, vcc
	v_cvt_pk_bf16_f32 v130, v92, v93
	v_cvt_pk_bf16_f32 v131, v94, v95
	v_cvt_pk_bf16_f32 v132, v88, v89
	v_cvt_pk_bf16_f32 v133, v90, v91
	global_store_dwordx4 v[134:135], v[130:133], off
	v_add_co_u32_e32 v134, vcc, s5, v128
	s_nop 0
	v_cvt_pk_bf16_f32 v130, v76, v77
	v_cvt_pk_bf16_f32 v131, v78, v79
	v_cvt_pk_bf16_f32 v132, v72, v73
	v_cvt_pk_bf16_f32 v133, v74, v75
	s_nop 0
	v_addc_co_u32_e32 v135, vcc, 0, v129, vcc
	global_store_dwordx4 v[134:135], v[130:133], off
	v_add_co_u32_e32 v134, vcc, s92, v128
	s_mov_b32 s5, 0xa000
	s_nop 0
	v_addc_co_u32_e32 v135, vcc, 0, v129, vcc
	v_cvt_pk_bf16_f32 v130, v116, v117
	v_cvt_pk_bf16_f32 v131, v118, v119
	v_cvt_pk_bf16_f32 v132, v112, v113
	v_cvt_pk_bf16_f32 v133, v114, v115
	global_store_dwordx4 v[134:135], v[130:133], off
	v_add_co_u32_e32 v134, vcc, s5, v128
	s_mov_b32 s5, 0xc000
	s_nop 0
	v_addc_co_u32_e32 v135, vcc, 0, v129, vcc
	v_cvt_pk_bf16_f32 v130, v100, v101
	v_cvt_pk_bf16_f32 v131, v102, v103
	v_cvt_pk_bf16_f32 v132, v96, v97
	v_cvt_pk_bf16_f32 v133, v98, v99
	global_store_dwordx4 v[134:135], v[130:133], off
	v_add_co_u32_e32 v134, vcc, s5, v128
	s_mov_b32 s5, 0xe000
	s_nop 0
	v_addc_co_u32_e32 v135, vcc, 0, v129, vcc
	v_cvt_pk_bf16_f32 v130, v84, v85
	v_cvt_pk_bf16_f32 v131, v86, v87
	v_cvt_pk_bf16_f32 v132, v80, v81
	v_cvt_pk_bf16_f32 v133, v82, v83
	global_store_dwordx4 v[134:135], v[130:133], off
	v_add_co_u32_e32 v134, vcc, s5, v128
	s_mov_b32 s5, 0x10000
	s_nop 0
	v_addc_co_u32_e32 v135, vcc, 0, v129, vcc
	v_cvt_pk_bf16_f32 v130, v68, v69
	v_cvt_pk_bf16_f32 v131, v70, v71
	v_cvt_pk_bf16_f32 v132, v64, v65
	v_cvt_pk_bf16_f32 v133, v66, v67
	global_store_dwordx4 v[134:135], v[130:133], off
	v_add_co_u32_e32 v134, vcc, s5, v128
	s_mov_b32 s5, 0x12000
	s_nop 0
	v_addc_co_u32_e32 v135, vcc, 0, v129, vcc
	v_cvt_pk_bf16_f32 v130, v60, v61
	v_cvt_pk_bf16_f32 v131, v62, v63
	v_cvt_pk_bf16_f32 v132, v56, v57
	v_cvt_pk_bf16_f32 v133, v58, v59
	global_store_dwordx4 v[134:135], v[130:133], off
	v_add_co_u32_e32 v134, vcc, s5, v128
	s_mov_b32 s5, 0x14000
	s_nop 0
	v_addc_co_u32_e32 v135, vcc, 0, v129, vcc
	v_cvt_pk_bf16_f32 v130, v44, v45
	v_cvt_pk_bf16_f32 v131, v46, v47
	v_cvt_pk_bf16_f32 v132, v40, v41
	v_cvt_pk_bf16_f32 v133, v42, v43
	global_store_dwordx4 v[134:135], v[130:133], off
	v_add_co_u32_e32 v134, vcc, s5, v128
	s_mov_b32 s5, 0x16000
	s_nop 0
	v_addc_co_u32_e32 v135, vcc, 0, v129, vcc
	v_cvt_pk_bf16_f32 v130, v28, v29
	v_cvt_pk_bf16_f32 v131, v30, v31
	v_cvt_pk_bf16_f32 v132, v24, v25
	v_cvt_pk_bf16_f32 v133, v26, v27
	global_store_dwordx4 v[134:135], v[130:133], off
	v_add_co_u32_e32 v134, vcc, s5, v128
	s_mov_b32 s5, 0x18000
	s_nop 0
	v_addc_co_u32_e32 v135, vcc, 0, v129, vcc
	v_cvt_pk_bf16_f32 v130, v12, v13
	v_cvt_pk_bf16_f32 v131, v14, v15
	v_cvt_pk_bf16_f32 v132, v8, v9
	v_cvt_pk_bf16_f32 v133, v10, v11
	global_store_dwordx4 v[134:135], v[130:133], off
	v_add_co_u32_e32 v134, vcc, s5, v128
	s_mov_b32 s5, 0x1a000
	s_nop 0
	v_addc_co_u32_e32 v135, vcc, 0, v129, vcc
	v_cvt_pk_bf16_f32 v130, v52, v53
	v_cvt_pk_bf16_f32 v131, v54, v55
	v_cvt_pk_bf16_f32 v132, v48, v49
	v_cvt_pk_bf16_f32 v133, v50, v51
	global_store_dwordx4 v[134:135], v[130:133], off
	v_add_co_u32_e32 v134, vcc, s5, v128
	s_mov_b32 s5, 0x1c000
	s_nop 0
	v_addc_co_u32_e32 v135, vcc, 0, v129, vcc
	v_cvt_pk_bf16_f32 v130, v36, v37
	v_cvt_pk_bf16_f32 v131, v38, v39
	v_cvt_pk_bf16_f32 v132, v32, v33
	v_cvt_pk_bf16_f32 v133, v34, v35
	global_store_dwordx4 v[134:135], v[130:133], off
	v_add_co_u32_e32 v134, vcc, s5, v128
	s_nop 0
	v_cvt_pk_bf16_f32 v130, v20, v21
	v_cvt_pk_bf16_f32 v131, v22, v23
	v_cvt_pk_bf16_f32 v132, v16, v17
	v_cvt_pk_bf16_f32 v133, v18, v19
	s_nop 0
	v_addc_co_u32_e32 v135, vcc, 0, v129, vcc
	v_add_co_u32_e32 v128, vcc, 0x1e000, v128
	global_store_dwordx4 v[134:135], v[130:133], off
	s_nop 0
	v_addc_co_u32_e32 v129, vcc, 0, v129, vcc
	v_cvt_pk_bf16_f32 v130, v4, v5
	v_cvt_pk_bf16_f32 v131, v6, v7
	v_cvt_pk_bf16_f32 v132, v0, v1
	v_cvt_pk_bf16_f32 v133, v2, v3
	global_store_dwordx4 v[128:129], v[130:133], off

.LBB0_1436:
	s_add_u32 s28, s6, 0xfffc0080
	s_addc_u32 s29, s7, -1
	s_add_i32 s71, 0, 0x10000
	v_add_u32_e32 v140, s71, v200
	ds_read_b128 v[128:131], v140
	ds_read_b128 v[132:135], v140 offset:1024
	ds_read_b128 v[136:139], v140 offset:2048
	ds_read_b128 v[140:143], v140 offset:3072
	s_cmp_eq_u32 s70, 12
	s_cselect_b32 s53, s17, s29
	s_cselect_b32 s52, s66, s28
	s_cselect_b32 s51, s13, s69
	s_cselect_b32 s50, s67, s68
	s_add_i32 m0, s56, 0xc000
	ds_read_b128 v[144:147], v201
	ds_read_b128 v[152:155], v201 offset:2048
	ds_read_b128 v[170:173], v201 offset:4096
	ds_read_b128 v[192:195], v201 offset:6144
	ds_read_b128 v[148:151], v201 offset:1024
	ds_read_b128 v[166:169], v201 offset:3072
	ds_read_b128 v[188:191], v201 offset:5120
	ds_read_b128 v[202:205], v201 offset:7168
	global_load_lds_dwordx4 v162, s[6:7]
	s_add_i32 m0, s56, 0xe000
	s_nop 0
	global_load_lds_dwordx4 v164, s[6:7]
	s_waitcnt lgkmcnt(8)
	s_barrier
	s_waitcnt lgkmcnt(7)
	v_mfma_f32_16x16x32_bf16 v[124:127], v[128:131], v[144:147], v[124:127]
	v_mfma_f32_16x16x32_bf16 v[116:119], v[136:139], v[144:147], v[116:119]
	s_waitcnt lgkmcnt(6)
	v_mfma_f32_16x16x32_bf16 v[108:111], v[128:131], v[152:155], v[108:111]
	v_mfma_f32_16x16x32_bf16 v[100:103], v[136:139], v[152:155], v[100:103]
	s_waitcnt lgkmcnt(5)
	v_mfma_f32_16x16x32_bf16 v[92:95], v[128:131], v[170:173], v[92:95]
	v_mfma_f32_16x16x32_bf16 v[84:87], v[136:139], v[170:173], v[84:87]
	s_waitcnt lgkmcnt(4)
	v_mfma_f32_16x16x32_bf16 v[76:79], v[128:131], v[192:195], v[76:79]
	v_mfma_f32_16x16x32_bf16 v[68:71], v[136:139], v[192:195], v[68:71]
	s_waitcnt lgkmcnt(3)
	v_mfma_f32_16x16x32_bf16 v[124:127], v[132:135], v[148:151], v[124:127]
	v_mfma_f32_16x16x32_bf16 v[116:119], v[140:143], v[148:151], v[116:119]
	s_waitcnt lgkmcnt(2)
	v_mfma_f32_16x16x32_bf16 v[108:111], v[132:135], v[166:169], v[108:111]
	v_mfma_f32_16x16x32_bf16 v[100:103], v[140:143], v[166:169], v[100:103]
	s_waitcnt lgkmcnt(1)
	v_mfma_f32_16x16x32_bf16 v[92:95], v[132:135], v[188:191], v[92:95]
	v_mfma_f32_16x16x32_bf16 v[84:87], v[140:143], v[188:191], v[84:87]
	s_waitcnt lgkmcnt(0)
	v_mfma_f32_16x16x32_bf16 v[76:79], v[132:135], v[202:205], v[76:79]
	v_mfma_f32_16x16x32_bf16 v[68:71], v[140:143], v[202:205], v[68:71]
	s_barrier
	s_add_i32 s28, 0, 0x14000
	v_add_u32_e32 v174, s28, v200
	s_add_i32 s29, s71, s55
	ds_read_b128 v[206:209], v174
	ds_read_b128 v[210:213], v174 offset:1024
	ds_read_b128 v[214:217], v174 offset:2048
	ds_read_b128 v[232:235], v174 offset:3072
	s_mov_b32 m0, s29
	s_nop 0
	global_load_lds_dwordx4 v176, s[50:51]
	s_add_i32 m0, s29, 0x2000
	s_nop 0
	global_load_lds_dwordx4 v160, s[50:51]
	s_barrier
	s_waitcnt lgkmcnt(3)
	v_mfma_f32_16x16x32_bf16 v[120:123], v[206:209], v[144:147], v[120:123]
	s_waitcnt lgkmcnt(1)
	v_mfma_f32_16x16x32_bf16 v[112:115], v[214:217], v[144:147], v[112:115]
	v_mfma_f32_16x16x32_bf16 v[104:107], v[206:209], v[152:155], v[104:107]
	v_mfma_f32_16x16x32_bf16 v[96:99], v[214:217], v[152:155], v[96:99]
	v_mfma_f32_16x16x32_bf16 v[88:91], v[206:209], v[170:173], v[88:91]
	v_mfma_f32_16x16x32_bf16 v[80:83], v[214:217], v[170:173], v[80:83]
	v_mfma_f32_16x16x32_bf16 v[72:75], v[206:209], v[192:195], v[72:75]
	v_mfma_f32_16x16x32_bf16 v[64:67], v[214:217], v[192:195], v[64:67]
	v_mfma_f32_16x16x32_bf16 v[120:123], v[210:213], v[148:151], v[120:123]
	s_waitcnt lgkmcnt(0)
	v_mfma_f32_16x16x32_bf16 v[112:115], v[232:235], v[148:151], v[112:115]
	v_mfma_f32_16x16x32_bf16 v[104:107], v[210:213], v[166:169], v[104:107]
	v_mfma_f32_16x16x32_bf16 v[96:99], v[232:235], v[166:169], v[96:99]
	v_mfma_f32_16x16x32_bf16 v[88:91], v[210:213], v[188:191], v[88:91]
	v_mfma_f32_16x16x32_bf16 v[80:83], v[232:235], v[188:191], v[80:83]
	v_mfma_f32_16x16x32_bf16 v[72:75], v[210:213], v[202:205], v[72:75]
	v_mfma_f32_16x16x32_bf16 v[64:67], v[232:235], v[202:205], v[64:67]
	s_mov_b32 m0, s56
	s_barrier
	ds_read_b128 v[144:147], v201 offset:16384
	ds_read_b128 v[152:155], v201 offset:18432
	ds_read_b128 v[170:173], v201 offset:20480
	ds_read_b128 v[192:195], v201 offset:22528
	ds_read_b128 v[148:151], v201 offset:17408
	ds_read_b128 v[166:169], v201 offset:19456
	ds_read_b128 v[188:191], v201 offset:21504
	ds_read_b128 v[202:205], v201 offset:23552
	global_load_lds_dwordx4 v156, s[52:53]
	s_mov_b32 m0, s57
	s_nop 0
	global_load_lds_dwordx4 v158, s[52:53]
	s_barrier
	s_waitcnt lgkmcnt(7)
	v_mfma_f32_16x16x32_bf16 v[60:63], v[128:131], v[144:147], v[60:63]
	v_mfma_f32_16x16x32_bf16 v[52:55], v[136:139], v[144:147], v[52:55]
	s_waitcnt lgkmcnt(6)
	v_mfma_f32_16x16x32_bf16 v[44:47], v[128:131], v[152:155], v[44:47]
	v_mfma_f32_16x16x32_bf16 v[36:39], v[136:139], v[152:155], v[36:39]
	s_waitcnt lgkmcnt(5)
	v_mfma_f32_16x16x32_bf16 v[28:31], v[128:131], v[170:173], v[28:31]
	v_mfma_f32_16x16x32_bf16 v[20:23], v[136:139], v[170:173], v[20:23]
	s_waitcnt lgkmcnt(4)
	v_mfma_f32_16x16x32_bf16 v[12:15], v[128:131], v[192:195], v[12:15]
	v_mfma_f32_16x16x32_bf16 v[4:7], v[136:139], v[192:195], v[4:7]
	s_waitcnt lgkmcnt(3)
	v_mfma_f32_16x16x32_bf16 v[60:63], v[132:135], v[148:151], v[60:63]
	v_mfma_f32_16x16x32_bf16 v[52:55], v[140:143], v[148:151], v[52:55]
	s_waitcnt lgkmcnt(2)
	v_mfma_f32_16x16x32_bf16 v[44:47], v[132:135], v[166:169], v[44:47]
	v_mfma_f32_16x16x32_bf16 v[36:39], v[140:143], v[166:169], v[36:39]
	s_waitcnt lgkmcnt(1)
	v_mfma_f32_16x16x32_bf16 v[28:31], v[132:135], v[188:191], v[28:31]
	v_mfma_f32_16x16x32_bf16 v[20:23], v[140:143], v[188:191], v[20:23]
	s_waitcnt lgkmcnt(0)
	v_mfma_f32_16x16x32_bf16 v[12:15], v[132:135], v[202:205], v[12:15]
	v_mfma_f32_16x16x32_bf16 v[4:7], v[140:143], v[202:205], v[4:7]
	s_barrier
	s_add_u32 s72, s50, 0x40000
	s_addc_u32 s73, s51, 0
	s_add_i32 s28, s28, s55
	s_mov_b32 m0, s28
	s_nop 0
	global_load_lds_dwordx4 v176, s[72:73]
	s_add_i32 m0, s28, 0x2000
	s_nop 0
	global_load_lds_dwordx4 v160, s[72:73]
	s_waitcnt vmcnt(6)
	s_barrier
	v_mfma_f32_16x16x32_bf16 v[56:59], v[206:209], v[144:147], v[56:59]
	v_mfma_f32_16x16x32_bf16 v[48:51], v[214:217], v[144:147], v[48:51]
	v_mfma_f32_16x16x32_bf16 v[40:43], v[206:209], v[152:155], v[40:43]
	v_mfma_f32_16x16x32_bf16 v[32:35], v[214:217], v[152:155], v[32:35]
	v_mfma_f32_16x16x32_bf16 v[24:27], v[206:209], v[170:173], v[24:27]
	v_mfma_f32_16x16x32_bf16 v[16:19], v[214:217], v[170:173], v[16:19]
	v_mfma_f32_16x16x32_bf16 v[8:11], v[206:209], v[192:195], v[8:11]
	v_mfma_f32_16x16x32_bf16 v[0:3], v[214:217], v[192:195], v[0:3]
	v_mfma_f32_16x16x32_bf16 v[56:59], v[210:213], v[148:151], v[56:59]
	v_mfma_f32_16x16x32_bf16 v[48:51], v[232:235], v[148:151], v[48:51]
	v_mfma_f32_16x16x32_bf16 v[40:43], v[210:213], v[166:169], v[40:43]
	v_mfma_f32_16x16x32_bf16 v[32:35], v[232:235], v[166:169], v[32:35]
	v_mfma_f32_16x16x32_bf16 v[24:27], v[210:213], v[188:191], v[24:27]
	v_mfma_f32_16x16x32_bf16 v[16:19], v[232:235], v[188:191], v[16:19]
	v_mfma_f32_16x16x32_bf16 v[8:11], v[210:213], v[202:205], v[8:11]
	v_mfma_f32_16x16x32_bf16 v[0:3], v[232:235], v[202:205], v[0:3]
	s_add_i32 s28, 0, 0x18000
	v_add_u32_e32 v140, s28, v200
	s_barrier
	ds_read_b128 v[128:131], v140
	ds_read_b128 v[132:135], v140 offset:1024
	ds_read_b128 v[136:139], v140 offset:2048
	ds_read_b128 v[140:143], v140 offset:3072
	s_add_u32 s52, s52, 0x40000
	s_addc_u32 s53, s53, 0
	s_mov_b32 m0, s58
	ds_read_b128 v[144:147], v201 offset:32768
	ds_read_b128 v[152:155], v201 offset:34816
	ds_read_b128 v[170:173], v201 offset:36864
	ds_read_b128 v[192:195], v201 offset:38912
	ds_read_b128 v[148:151], v201 offset:33792
	ds_read_b128 v[166:169], v201 offset:35840
	ds_read_b128 v[188:191], v201 offset:37888
	ds_read_b128 v[202:205], v201 offset:39936
	global_load_lds_dwordx4 v156, s[52:53]
	s_mov_b32 m0, s59
	s_nop 0
	global_load_lds_dwordx4 v158, s[52:53]
	s_waitcnt lgkmcnt(8)
	s_barrier
	s_waitcnt lgkmcnt(7)
	v_mfma_f32_16x16x32_bf16 v[124:127], v[128:131], v[144:147], v[124:127]
	v_mfma_f32_16x16x32_bf16 v[116:119], v[136:139], v[144:147], v[116:119]
	s_waitcnt lgkmcnt(6)
	v_mfma_f32_16x16x32_bf16 v[108:111], v[128:131], v[152:155], v[108:111]
	v_mfma_f32_16x16x32_bf16 v[100:103], v[136:139], v[152:155], v[100:103]
	s_waitcnt lgkmcnt(5)
	v_mfma_f32_16x16x32_bf16 v[92:95], v[128:131], v[170:173], v[92:95]
	v_mfma_f32_16x16x32_bf16 v[84:87], v[136:139], v[170:173], v[84:87]
	s_waitcnt lgkmcnt(4)
	v_mfma_f32_16x16x32_bf16 v[76:79], v[128:131], v[192:195], v[76:79]
	v_mfma_f32_16x16x32_bf16 v[68:71], v[136:139], v[192:195], v[68:71]
	s_waitcnt lgkmcnt(3)
	v_mfma_f32_16x16x32_bf16 v[124:127], v[132:135], v[148:151], v[124:127]
	v_mfma_f32_16x16x32_bf16 v[116:119], v[140:143], v[148:151], v[116:119]
	s_waitcnt lgkmcnt(2)
	v_mfma_f32_16x16x32_bf16 v[108:111], v[132:135], v[166:169], v[108:111]
	v_mfma_f32_16x16x32_bf16 v[100:103], v[140:143], v[166:169], v[100:103]
	s_waitcnt lgkmcnt(1)
	v_mfma_f32_16x16x32_bf16 v[92:95], v[132:135], v[188:191], v[92:95]
	v_mfma_f32_16x16x32_bf16 v[84:87], v[140:143], v[188:191], v[84:87]
	s_waitcnt lgkmcnt(0)
	v_mfma_f32_16x16x32_bf16 v[76:79], v[132:135], v[202:205], v[76:79]
	v_mfma_f32_16x16x32_bf16 v[68:71], v[140:143], v[202:205], v[68:71]
	s_barrier
	s_add_i32 s29, 0, 0x1c000
	s_add_i32 s28, s28, s55
	v_add_u32_e32 v232, s29, v200
	s_mov_b32 m0, s28
	ds_read_b128 v[206:209], v232
	ds_read_b128 v[210:213], v232 offset:1024
	ds_read_b128 v[214:217], v232 offset:2048
	ds_read_b128 v[232:235], v232 offset:3072
	s_add_u32 s98, s50, 0x80
	s_addc_u32 s99, s51, 0
	global_load_lds_dwordx4 v176, s[98:99]
	s_add_i32 m0, s28, 0x2000
	s_nop 0
	global_load_lds_dwordx4 v160, s[98:99]
	s_barrier
	s_waitcnt lgkmcnt(3)
	v_mfma_f32_16x16x32_bf16 v[120:123], v[206:209], v[144:147], v[120:123]
	s_waitcnt lgkmcnt(1)
	v_mfma_f32_16x16x32_bf16 v[112:115], v[214:217], v[144:147], v[112:115]
	v_mfma_f32_16x16x32_bf16 v[104:107], v[206:209], v[152:155], v[104:107]
	v_mfma_f32_16x16x32_bf16 v[96:99], v[214:217], v[152:155], v[96:99]
	v_mfma_f32_16x16x32_bf16 v[88:91], v[206:209], v[170:173], v[88:91]
	v_mfma_f32_16x16x32_bf16 v[80:83], v[214:217], v[170:173], v[80:83]
	v_mfma_f32_16x16x32_bf16 v[72:75], v[206:209], v[192:195], v[72:75]
	v_mfma_f32_16x16x32_bf16 v[64:67], v[214:217], v[192:195], v[64:67]
	v_mfma_f32_16x16x32_bf16 v[120:123], v[210:213], v[148:151], v[120:123]
	s_waitcnt lgkmcnt(0)
	v_mfma_f32_16x16x32_bf16 v[112:115], v[232:235], v[148:151], v[112:115]
	v_mfma_f32_16x16x32_bf16 v[104:107], v[210:213], v[166:169], v[104:107]
	v_mfma_f32_16x16x32_bf16 v[96:99], v[232:235], v[166:169], v[96:99]
	v_mfma_f32_16x16x32_bf16 v[88:91], v[210:213], v[188:191], v[88:91]
	v_mfma_f32_16x16x32_bf16 v[80:83], v[232:235], v[188:191], v[80:83]
	v_mfma_f32_16x16x32_bf16 v[72:75], v[210:213], v[202:205], v[72:75]
	v_mfma_f32_16x16x32_bf16 v[64:67], v[232:235], v[202:205], v[64:67]
	s_mov_b32 m0, s62
	s_barrier
	ds_read_b128 v[144:147], v201 offset:49152
	ds_read_b128 v[152:155], v201 offset:51200
	ds_read_b128 v[170:173], v201 offset:53248
	ds_read_b128 v[192:195], v201 offset:55296
	ds_read_b128 v[148:151], v201 offset:50176
	ds_read_b128 v[166:169], v201 offset:52224
	ds_read_b128 v[188:191], v201 offset:54272
	ds_read_b128 v[202:205], v201 offset:56320
	s_add_u32 s98, s52, 0xfffc0080
	s_addc_u32 s99, s53, -1
	global_load_lds_dwordx4 v156, s[98:99]
	s_mov_b32 m0, s63
	s_nop 0
	global_load_lds_dwordx4 v158, s[98:99]
	s_barrier
	s_waitcnt lgkmcnt(7)
	v_mfma_f32_16x16x32_bf16 v[60:63], v[128:131], v[144:147], v[60:63]
	v_mfma_f32_16x16x32_bf16 v[52:55], v[136:139], v[144:147], v[52:55]
	s_waitcnt lgkmcnt(6)
	v_mfma_f32_16x16x32_bf16 v[44:47], v[128:131], v[152:155], v[44:47]
	v_mfma_f32_16x16x32_bf16 v[36:39], v[136:139], v[152:155], v[36:39]
	s_waitcnt lgkmcnt(5)
	v_mfma_f32_16x16x32_bf16 v[28:31], v[128:131], v[170:173], v[28:31]
	v_mfma_f32_16x16x32_bf16 v[20:23], v[136:139], v[170:173], v[20:23]
	s_waitcnt lgkmcnt(4)
	v_mfma_f32_16x16x32_bf16 v[12:15], v[128:131], v[192:195], v[12:15]
	v_mfma_f32_16x16x32_bf16 v[4:7], v[136:139], v[192:195], v[4:7]
	s_waitcnt lgkmcnt(3)
	v_mfma_f32_16x16x32_bf16 v[60:63], v[132:135], v[148:151], v[60:63]
	v_mfma_f32_16x16x32_bf16 v[52:55], v[140:143], v[148:151], v[52:55]
	s_waitcnt lgkmcnt(2)
	v_mfma_f32_16x16x32_bf16 v[44:47], v[132:135], v[166:169], v[44:47]
	v_mfma_f32_16x16x32_bf16 v[36:39], v[140:143], v[166:169], v[36:39]
	s_waitcnt lgkmcnt(1)
	v_mfma_f32_16x16x32_bf16 v[28:31], v[132:135], v[188:191], v[28:31]
	v_mfma_f32_16x16x32_bf16 v[20:23], v[140:143], v[188:191], v[20:23]
	s_waitcnt lgkmcnt(0)
	v_mfma_f32_16x16x32_bf16 v[12:15], v[132:135], v[202:205], v[12:15]
	v_mfma_f32_16x16x32_bf16 v[4:7], v[140:143], v[202:205], v[4:7]
	s_barrier
	s_add_u32 s50, s50, 0x40080
	s_addc_u32 s51, s51, 0
	s_add_i32 s28, s29, s55
	s_mov_b32 m0, s28
	s_nop 0
	global_load_lds_dwordx4 v176, s[50:51]
	s_add_i32 m0, s28, 0x2000
	s_nop 0
	global_load_lds_dwordx4 v160, s[50:51]
	s_waitcnt vmcnt(6)
	s_barrier
	v_mfma_f32_16x16x32_bf16 v[56:59], v[206:209], v[144:147], v[56:59]
	v_mfma_f32_16x16x32_bf16 v[48:51], v[214:217], v[144:147], v[48:51]
	v_mfma_f32_16x16x32_bf16 v[40:43], v[206:209], v[152:155], v[40:43]
	v_mfma_f32_16x16x32_bf16 v[32:35], v[214:217], v[152:155], v[32:35]
	v_mfma_f32_16x16x32_bf16 v[24:27], v[206:209], v[170:173], v[24:27]
	v_mfma_f32_16x16x32_bf16 v[16:19], v[214:217], v[170:173], v[16:19]
	v_mfma_f32_16x16x32_bf16 v[8:11], v[206:209], v[192:195], v[8:11]
	v_mfma_f32_16x16x32_bf16 v[0:3], v[214:217], v[192:195], v[0:3]
	v_mfma_f32_16x16x32_bf16 v[56:59], v[210:213], v[148:151], v[56:59]
	v_mfma_f32_16x16x32_bf16 v[48:51], v[232:235], v[148:151], v[48:51]
	v_mfma_f32_16x16x32_bf16 v[40:43], v[210:213], v[166:169], v[40:43]
	v_mfma_f32_16x16x32_bf16 v[32:35], v[232:235], v[166:169], v[32:35]
	v_mfma_f32_16x16x32_bf16 v[24:27], v[210:213], v[188:191], v[24:27]
	v_mfma_f32_16x16x32_bf16 v[16:19], v[232:235], v[188:191], v[16:19]
	v_mfma_f32_16x16x32_bf16 v[8:11], v[210:213], v[202:205], v[8:11]
	v_mfma_f32_16x16x32_bf16 v[0:3], v[232:235], v[202:205], v[0:3]
	s_add_i32 s70, s70, 2
	s_add_u32 s6, s6, 0x100
	s_addc_u32 s7, s7, 0
	s_add_u32 s68, s68, 0x100
	s_addc_u32 s69, s69, 0
	s_cmp_lt_u32 s70, 14
	s_barrier
	s_cbranch_scc1 .LBB0_1436
	v_mov_b32_e32 v134, v199
	v_mov_b32_e32 v128, v198
	s_lshl_b32 s4, s4, 8
	s_add_i32 s4, s4, s60
	v_add_u32_e32 v192, s4, v128
	v_lshlrev_b32_e32 v128, 2, v134
	v_ashrrev_i32_e32 v129, 31, v128
	v_ashrrev_i32_e32 v193, 31, v192
	v_add_u32_e32 v190, 16, v192
	v_lshl_add_u64 v[132:133], v[128:129], 2, s[8:9]
	v_lshlrev_b64 v[128:129], 6, v[192:193]
	v_ashrrev_i32_e32 v191, 31, v190
	v_add_u32_e32 v188, 32, v192
	v_lshl_add_u64 v[128:129], v[132:133], 0, v[128:129]
	v_lshlrev_b64 v[130:131], 6, v[190:191]
	v_ashrrev_i32_e32 v189, 31, v188
	v_lshl_add_u64 v[130:131], v[132:133], 0, v[130:131]
	global_load_dwordx4 v[202:205], v[128:129], off
	global_load_dwordx4 v[144:147], v[130:131], off
	v_lshlrev_b64 v[128:129], 6, v[188:189]
	v_add_u32_e32 v174, 48, v192
	v_lshl_add_u64 v[128:129], v[132:133], 0, v[128:129]
	v_ashrrev_i32_e32 v175, 31, v174
	global_load_dwordx4 v[148:151], v[128:129], off
	v_lshlrev_b64 v[128:129], 6, v[174:175]
	v_lshl_add_u64 v[128:129], v[132:133], 0, v[128:129]
	global_load_dwordx4 v[152:155], v[128:129], off
	v_add_u32_e32 v172, 0x80, v192
	v_ashrrev_i32_e32 v173, 31, v172
	v_lshlrev_b64 v[128:129], 6, v[172:173]
	v_lshl_add_u64 v[128:129], v[132:133], 0, v[128:129]
	global_load_dwordx4 v[140:143], v[128:129], off
	v_add_u32_e32 v170, 0x90, v192
	v_ashrrev_i32_e32 v171, 31, v170
	v_lshlrev_b64 v[128:129], 6, v[170:171]
	v_lshl_add_u64 v[128:129], v[132:133], 0, v[128:129]
	global_load_dwordx4 v[128:131], v[128:129], off
	s_lshl_b32 s5, s5, 7
	v_add_u32_e32 v168, 0xa0, v192
	v_add_u32_e32 v166, 0xb0, v192
	s_or_b32 s5, s5, s61
	v_ashrrev_i32_e32 v169, 31, v168
	v_ashrrev_i32_e32 v167, 31, v166
	v_lshl_add_u32 v194, v134, 3, s5
	v_lshlrev_b64 v[134:135], 6, v[168:169]
	v_lshlrev_b64 v[136:137], 6, v[166:167]
	v_lshl_add_u64 v[134:135], v[132:133], 0, v[134:135]
	v_lshl_add_u64 v[132:133], v[132:133], 0, v[136:137]
	global_load_dwordx4 v[136:139], v[134:135], off
	s_nop 0
	global_load_dwordx4 v[132:135], v[132:133], off
	s_mov_b32 s4, 0x358637bd
	v_mov_b64_e32 v[196:197], s[4:5]
	v_ashrrev_i32_e32 v195, 31, v194
	s_mov_b64 s[50:51], s[20:21]
	s_waitcnt vmcnt(0)
	v_mov_b32_e32 v206, v203
	v_mov_b32_e32 v207, v204
	v_mov_b32_e32 v203, v205
	v_mov_b32_e32 v204, v145
	v_mov_b32_e32 v205, v146
	v_mov_b32_e32 v145, v147
	v_pk_add_f32 v[202:203], v[206:207], v[202:203]
	v_mov_b32_e32 v146, v149
	v_mov_b32_e32 v147, v150
	v_mov_b32_e32 v149, v151
	v_mov_b32_e32 v150, v153
	v_mov_b32_e32 v151, v154
	v_mov_b32_e32 v153, v155
	v_pk_add_f32 v[144:145], v[204:205], v[144:145]
	v_mov_b32_e32 v155, v202
	v_pk_add_f32 v[146:147], v[146:147], v[148:149]
	v_pk_add_f32 v[148:149], v[150:151], v[152:153]
	v_mov_b32_e32 v154, v144
	v_mov_b32_e32 v202, v145
	v_mov_b32_e32 v144, v148
	v_mov_b32_e32 v145, v146
	v_mov_b32_e32 v146, v149
	v_pk_add_f32 v[148:149], v[154:155], v[202:203]
	v_pk_add_f32 v[144:145], v[144:145], v[146:147]
	ds_bpermute_b32 v147, v219, v149
	ds_bpermute_b32 v146, v219, v148
	ds_bpermute_b32 v151, v219, v145
	ds_bpermute_b32 v150, v219, v144
	v_mov_b32_e32 v152, v141
	v_mov_b32_e32 v153, v142
	v_mov_b32_e32 v141, v143
	s_waitcnt lgkmcnt(0)
	v_pk_add_f32 v[142:143], v[148:149], v[146:147]
	ds_bpermute_b32 v147, v218, v143
	ds_bpermute_b32 v146, v218, v142
	v_pk_add_f32 v[144:145], v[144:145], v[150:151]
	ds_bpermute_b32 v149, v218, v145
	ds_bpermute_b32 v148, v218, v144
	v_mov_b32_e32 v150, v129
	s_waitcnt lgkmcnt(2)
	v_pk_add_f32 v[142:143], v[142:143], v[146:147]
	v_mov_b32_e32 v151, v130
	v_pk_fma_f32 v[142:143], v[142:143], s[30:31], v[196:197] op_sel_hi:[1,0,0]
	s_waitcnt lgkmcnt(0)
	v_pk_add_f32 v[144:145], v[144:145], v[148:149]
	v_mul_f32_e32 v129, 0x4b800000, v143
	v_cmp_gt_f32_e32 vcc, s86, v143
	v_pk_fma_f32 v[146:147], v[144:145], s[30:31], v[196:197] op_sel_hi:[1,0,0]
	v_mul_f32_e32 v130, 0x4b800000, v142
	v_cndmask_b32_e32 v129, v143, v129, vcc
	v_rsq_f32_e32 v129, v129
	v_cmp_gt_f32_e64 s[4:5], s86, v142
	v_mul_f32_e32 v144, 0x4b800000, v147
	v_cmp_gt_f32_e64 s[6:7], s86, v147
	v_cndmask_b32_e64 v130, v142, v130, s[4:5]
	v_rsq_f32_e32 v142, v130
	v_cndmask_b32_e64 v130, v147, v144, s[6:7]
	v_rsq_f32_e32 v143, v130
	v_mul_f32_e32 v130, 0x45800000, v129
	v_cndmask_b32_e32 v144, v129, v130, vcc
	v_mov_b32_e32 v129, v131
	v_pk_add_f32 v[140:141], v[152:153], v[140:141]
	v_pk_add_f32 v[128:129], v[150:151], v[128:129]
	v_mov_b32_e32 v131, v140
	v_mov_b32_e32 v130, v128
	v_mov_b32_e32 v140, v129
	v_pk_add_f32 v[128:129], v[130:131], v[140:141]
	ds_bpermute_b32 v131, v219, v129
	ds_bpermute_b32 v130, v219, v128
	v_mul_f32_e32 v145, 0x45800000, v142
	v_cndmask_b32_e64 v142, v142, v145, s[4:5]
	v_mul_f32_e32 v140, 0x4b800000, v146
	v_cmp_gt_f32_e32 vcc, s86, v146
	s_waitcnt lgkmcnt(0)
	v_pk_add_f32 v[128:129], v[128:129], v[130:131]
	ds_bpermute_b32 v131, v218, v129
	ds_bpermute_b32 v130, v218, v128
	v_cndmask_b32_e32 v140, v146, v140, vcc
	v_rsq_f32_e32 v141, v140
	v_mul_f32_e32 v140, 0x45800000, v143
	v_cndmask_b32_e64 v140, v143, v140, s[6:7]
	s_waitcnt lgkmcnt(0)
	v_pk_add_f32 v[128:129], v[128:129], v[130:131]
	v_mov_b32_e32 v131, v138
	v_pk_fma_f32 v[128:129], v[128:129], s[30:31], v[196:197] op_sel_hi:[1,0,0]
	v_mul_f32_e32 v143, 0x45800000, v141
	v_mul_f32_e32 v130, 0x4b800000, v129
	v_cmp_gt_f32_e64 s[4:5], s86, v129
	v_cmp_gt_f32_e64 s[6:7], s86, v128
	v_pk_mul_f32 v[110:111], v[110:111], v[142:143] op_sel_hi:[1,0]
	v_cndmask_b32_e64 v129, v129, v130, s[4:5]
	v_mov_b32_e32 v130, v137
	v_mov_b32_e32 v137, v139
	v_pk_add_f32 v[130:131], v[130:131], v[136:137]
	v_mov_b32_e32 v136, v133
	v_mov_b32_e32 v137, v134
	v_mov_b32_e32 v133, v135
	v_pk_add_f32 v[132:133], v[136:137], v[132:133]
	v_mov_b32_e32 v135, v130
	v_mov_b32_e32 v134, v132
	v_mov_b32_e32 v130, v133
	v_pk_add_f32 v[130:131], v[134:135], v[130:131]
	ds_bpermute_b32 v133, v219, v131
	ds_bpermute_b32 v132, v219, v130
	v_rsq_f32_e32 v145, v129
	v_mul_f32_e32 v129, 0x4b800000, v128
	v_cndmask_b32_e64 v128, v128, v129, s[6:7]
	v_rsq_f32_e32 v135, v128
	s_waitcnt lgkmcnt(0)
	v_pk_add_f32 v[128:129], v[130:131], v[132:133]
	ds_bpermute_b32 v131, v218, v129
	ds_bpermute_b32 v130, v218, v128
	v_pk_mul_f32 v[126:127], v[126:127], v[144:145] op_sel_hi:[1,0]
	v_pk_mul_f32 v[122:123], v[122:123], v[144:145] op_sel_hi:[1,0]
	v_pk_mul_f32 v[116:117], v[116:117], v[144:145] op_sel_hi:[1,0]
	v_pk_mul_f32 v[124:125], v[124:125], v[144:145] op_sel_hi:[1,0]
	v_pk_mul_f32 v[138:139], v[126:127], s[44:45] op_sel_hi:[1,0]
	v_pk_mul_f32 v[120:121], v[120:121], v[144:145] op_sel_hi:[1,0]
	v_pk_mul_f32 v[122:123], v[126:127], v[122:123]
	v_pk_mul_f32 v[118:119], v[118:119], v[144:145] op_sel_hi:[1,0]
	v_pk_mul_f32 v[126:127], v[116:117], s[44:45] op_sel_hi:[1,0]
	v_pk_mul_f32 v[146:147], v[124:125], s[44:45] op_sel_hi:[1,0]
	v_pk_mul_f32 v[120:121], v[124:125], v[120:121]
	v_pk_mul_f32 v[124:125], v[118:119], s[44:45] op_sel_hi:[1,0]
	v_exp_f32_e32 v126, v126
	v_exp_f32_e32 v127, v127
	s_waitcnt lgkmcnt(0)
	v_pk_add_f32 v[128:129], v[128:129], v[130:131]
	v_exp_f32_e32 v146, v146
	v_exp_f32_e32 v138, v138
	v_exp_f32_e32 v139, v139
	v_exp_f32_e32 v147, v147
	v_exp_f32_e32 v124, v124
	v_exp_f32_e32 v125, v125
	v_pk_fma_f32 v[128:129], v[128:129], s[30:31], v[196:197] op_sel_hi:[1,0,0]
	v_cndmask_b32_e32 v136, v141, v143, vcc
	v_mul_f32_e32 v132, 0x45800000, v145
	v_mul_f32_e32 v130, 0x4b800000, v129
	v_cmp_gt_f32_e32 vcc, s86, v129
	v_cndmask_b32_e64 v134, v145, v132, s[4:5]
	v_cmp_gt_f32_e64 s[4:5], s86, v128
	v_cndmask_b32_e32 v129, v129, v130, vcc
	v_mul_f32_e32 v130, 0x4b800000, v128
	v_pk_add_f32 v[126:127], v[126:127], 1.0 op_sel_hi:[1,0]
	v_rsq_f32_e32 v129, v129
	v_cndmask_b32_e64 v128, v128, v130, s[4:5]
	v_pk_add_f32 v[138:139], v[138:139], 1.0 op_sel_hi:[1,0]
	v_pk_add_f32 v[146:147], v[146:147], 1.0 op_sel_hi:[1,0]
	v_pk_add_f32 v[124:125], v[124:125], 1.0 op_sel_hi:[1,0]
	v_rcp_f32_e32 v126, v126
	v_rcp_f32_e32 v127, v127
	v_rsq_f32_e32 v128, v128
	v_rcp_f32_e32 v146, v146
	v_rcp_f32_e32 v138, v138
	v_rcp_f32_e32 v139, v139
	v_rcp_f32_e32 v147, v147
	v_rcp_f32_e32 v124, v124
	v_rcp_f32_e32 v125, v125
	v_pk_mul_f32 v[112:113], v[112:113], v[144:145] op_sel_hi:[1,0]
	v_pk_mul_f32 v[114:115], v[114:115], v[144:145] op_sel_hi:[1,0]
	v_pk_mul_f32 v[112:113], v[116:117], v[112:113]
	v_mul_f32_e32 v130, 0x45800000, v129
	v_pk_mul_f32 v[114:115], v[118:119], v[114:115]
	v_pk_mul_f32 v[112:113], v[112:113], v[126:127]
	v_cndmask_b32_e32 v130, v129, v130, vcc
	v_mul_f32_e32 v129, 0x45800000, v128
	v_pk_mul_f32 v[122:123], v[122:123], v[138:139]
	v_pk_mul_f32 v[120:121], v[120:121], v[146:147]
	v_pk_mul_f32 v[114:115], v[114:115], v[124:125]
	v_cvt_pk_bf16_f32 v116, v120, v121
	v_cvt_pk_bf16_f32 v117, v122, v123
	v_cvt_pk_bf16_f32 v118, v112, v113
	v_mov_b64_e32 v[112:113], s[10:11]
	v_cndmask_b32_e64 v128, v128, v129, s[4:5]
	v_cvt_pk_bf16_f32 v119, v114, v115
	v_mad_i64_i32 v[120:121], s[4:5], v192, s35, v[112:113]
	v_lshlrev_b64 v[114:115], 1, v[194:195]
	v_lshl_add_u64 v[120:121], v[120:121], 0, v[114:115]
	v_pk_mul_f32 v[108:109], v[108:109], v[142:143] op_sel_hi:[1,0]
	v_pk_mul_f32 v[106:107], v[106:107], v[142:143] op_sel_hi:[1,0]
	v_pk_mul_f32 v[104:105], v[104:105], v[142:143] op_sel_hi:[1,0]
	v_pk_mul_f32 v[102:103], v[102:103], v[142:143] op_sel_hi:[1,0]
	v_pk_mul_f32 v[100:101], v[100:101], v[142:143] op_sel_hi:[1,0]
	global_store_dwordx4 v[120:121], v[116:119], off
	v_pk_mul_f32 v[104:105], v[108:109], v[104:105]
	v_pk_mul_f32 v[106:107], v[110:111], v[106:107]
	v_pk_mul_f32 v[116:117], v[110:111], s[44:45] op_sel_hi:[1,0]
	v_pk_mul_f32 v[118:119], v[108:109], s[44:45] op_sel_hi:[1,0]
	v_pk_mul_f32 v[108:109], v[102:103], s[44:45] op_sel_hi:[1,0]
	v_pk_mul_f32 v[110:111], v[100:101], s[44:45] op_sel_hi:[1,0]
	v_exp_f32_e32 v108, v108
	v_exp_f32_e32 v110, v110
	v_exp_f32_e32 v109, v109
	v_exp_f32_e32 v111, v111
	v_exp_f32_e32 v118, v118
	v_exp_f32_e32 v116, v116
	v_exp_f32_e32 v117, v117
	v_exp_f32_e32 v119, v119
	v_pk_add_f32 v[108:109], v[108:109], 1.0 op_sel_hi:[1,0]
	v_pk_add_f32 v[110:111], v[110:111], 1.0 op_sel_hi:[1,0]
	v_pk_add_f32 v[116:117], v[116:117], 1.0 op_sel_hi:[1,0]
	v_pk_add_f32 v[118:119], v[118:119], 1.0 op_sel_hi:[1,0]
	v_rcp_f32_e32 v110, v110
	v_rcp_f32_e32 v108, v108
	v_rcp_f32_e32 v109, v109
	v_rcp_f32_e32 v111, v111
	v_rcp_f32_e32 v118, v118
	v_rcp_f32_e32 v116, v116
	v_rcp_f32_e32 v117, v117
	v_rcp_f32_e32 v119, v119
	v_pk_mul_f32 v[98:99], v[98:99], v[142:143] op_sel_hi:[1,0]
	v_pk_mul_f32 v[96:97], v[96:97], v[142:143] op_sel_hi:[1,0]
	v_pk_mul_f32 v[98:99], v[102:103], v[98:99]
	v_pk_mul_f32 v[96:97], v[100:101], v[96:97]
	v_pk_mul_f32 v[100:101], v[98:99], v[108:109]
	v_pk_mul_f32 v[98:99], v[96:97], v[110:111]
	v_pk_mul_f32 v[106:107], v[106:107], v[116:117]
	v_pk_mul_f32 v[104:105], v[104:105], v[118:119]
	v_pk_mul_f32 v[94:95], v[94:95], v[140:141] op_sel_hi:[1,0]
	v_cvt_pk_bf16_f32 v96, v104, v105
	v_cvt_pk_bf16_f32 v97, v106, v107
	v_cvt_pk_bf16_f32 v98, v98, v99
	v_cvt_pk_bf16_f32 v99, v100, v101
	v_mad_i64_i32 v[100:101], s[4:5], v190, s35, v[112:113]
	v_lshl_add_u64 v[100:101], v[100:101], 0, v[114:115]
	v_pk_mul_f32 v[92:93], v[92:93], v[140:141] op_sel_hi:[1,0]
	v_pk_mul_f32 v[90:91], v[90:91], v[140:141] op_sel_hi:[1,0]
	v_pk_mul_f32 v[88:89], v[88:89], v[140:141] op_sel_hi:[1,0]
	v_pk_mul_f32 v[86:87], v[86:87], v[140:141] op_sel_hi:[1,0]
	v_pk_mul_f32 v[84:85], v[84:85], v[140:141] op_sel_hi:[1,0]
	global_store_dwordx4 v[100:101], v[96:99], off
	v_pk_mul_f32 v[88:89], v[92:93], v[88:89]
	v_pk_mul_f32 v[90:91], v[94:95], v[90:91]
	v_pk_mul_f32 v[96:97], v[94:95], s[44:45] op_sel_hi:[1,0]
	v_pk_mul_f32 v[98:99], v[92:93], s[44:45] op_sel_hi:[1,0]
	v_pk_mul_f32 v[92:93], v[86:87], s[44:45] op_sel_hi:[1,0]
	v_pk_mul_f32 v[94:95], v[84:85], s[44:45] op_sel_hi:[1,0]
	v_exp_f32_e32 v92, v92
	v_exp_f32_e32 v94, v94
	v_exp_f32_e32 v93, v93
	v_exp_f32_e32 v95, v95
	v_exp_f32_e32 v98, v98
	v_exp_f32_e32 v96, v96
	v_exp_f32_e32 v97, v97
	v_exp_f32_e32 v99, v99
	v_pk_add_f32 v[92:93], v[92:93], 1.0 op_sel_hi:[1,0]
	v_pk_add_f32 v[94:95], v[94:95], 1.0 op_sel_hi:[1,0]
	v_pk_add_f32 v[96:97], v[96:97], 1.0 op_sel_hi:[1,0]
	v_pk_add_f32 v[98:99], v[98:99], 1.0 op_sel_hi:[1,0]
	v_rcp_f32_e32 v94, v94
	v_rcp_f32_e32 v92, v92
	v_rcp_f32_e32 v93, v93
	v_rcp_f32_e32 v95, v95
	v_rcp_f32_e32 v98, v98
	v_rcp_f32_e32 v96, v96
	v_rcp_f32_e32 v97, v97
	v_rcp_f32_e32 v99, v99
	v_pk_mul_f32 v[82:83], v[82:83], v[140:141] op_sel_hi:[1,0]
	v_pk_mul_f32 v[80:81], v[80:81], v[140:141] op_sel_hi:[1,0]
	v_pk_mul_f32 v[82:83], v[86:87], v[82:83]
	v_pk_mul_f32 v[80:81], v[84:85], v[80:81]
	v_pk_mul_f32 v[84:85], v[82:83], v[92:93]
	v_pk_mul_f32 v[82:83], v[80:81], v[94:95]
	v_pk_mul_f32 v[90:91], v[90:91], v[96:97]
	v_pk_mul_f32 v[88:89], v[88:89], v[98:99]
	v_pk_mul_f32 v[78:79], v[78:79], v[136:137] op_sel_hi:[1,0]
	v_cvt_pk_bf16_f32 v80, v88, v89
	v_cvt_pk_bf16_f32 v81, v90, v91
	v_cvt_pk_bf16_f32 v82, v82, v83
	v_cvt_pk_bf16_f32 v83, v84, v85
	v_mad_i64_i32 v[84:85], s[4:5], v188, s35, v[112:113]
	v_lshl_add_u64 v[84:85], v[84:85], 0, v[114:115]
	v_pk_mul_f32 v[76:77], v[76:77], v[136:137] op_sel_hi:[1,0]
	v_pk_mul_f32 v[74:75], v[74:75], v[136:137] op_sel_hi:[1,0]
	v_pk_mul_f32 v[72:73], v[72:73], v[136:137] op_sel_hi:[1,0]
	v_pk_mul_f32 v[70:71], v[70:71], v[136:137] op_sel_hi:[1,0]
	v_pk_mul_f32 v[68:69], v[68:69], v[136:137] op_sel_hi:[1,0]
	global_store_dwordx4 v[84:85], v[80:83], off
	v_pk_mul_f32 v[72:73], v[76:77], v[72:73]
	v_pk_mul_f32 v[74:75], v[78:79], v[74:75]
	v_pk_mul_f32 v[80:81], v[78:79], s[44:45] op_sel_hi:[1,0]
	v_pk_mul_f32 v[82:83], v[76:77], s[44:45] op_sel_hi:[1,0]
	v_pk_mul_f32 v[76:77], v[70:71], s[44:45] op_sel_hi:[1,0]
	v_pk_mul_f32 v[78:79], v[68:69], s[44:45] op_sel_hi:[1,0]
	v_exp_f32_e32 v76, v76
	v_exp_f32_e32 v78, v78
	v_exp_f32_e32 v77, v77
	v_exp_f32_e32 v79, v79
	v_exp_f32_e32 v82, v82
	v_exp_f32_e32 v80, v80
	v_exp_f32_e32 v81, v81
	v_exp_f32_e32 v83, v83
	v_pk_add_f32 v[76:77], v[76:77], 1.0 op_sel_hi:[1,0]
	v_pk_add_f32 v[78:79], v[78:79], 1.0 op_sel_hi:[1,0]
	v_pk_add_f32 v[80:81], v[80:81], 1.0 op_sel_hi:[1,0]
	v_pk_add_f32 v[82:83], v[82:83], 1.0 op_sel_hi:[1,0]
	v_rcp_f32_e32 v78, v78
	v_rcp_f32_e32 v76, v76
	v_rcp_f32_e32 v77, v77
	v_rcp_f32_e32 v79, v79
	v_rcp_f32_e32 v82, v82
	v_rcp_f32_e32 v80, v80
	v_rcp_f32_e32 v81, v81
	v_rcp_f32_e32 v83, v83
	v_pk_mul_f32 v[66:67], v[66:67], v[136:137] op_sel_hi:[1,0]
	v_pk_mul_f32 v[64:65], v[64:65], v[136:137] op_sel_hi:[1,0]
	v_pk_mul_f32 v[66:67], v[70:71], v[66:67]
	v_pk_mul_f32 v[64:65], v[68:69], v[64:65]
	v_pk_mul_f32 v[68:69], v[66:67], v[76:77]
	v_pk_mul_f32 v[66:67], v[64:65], v[78:79]
	v_pk_mul_f32 v[74:75], v[74:75], v[80:81]
	v_pk_mul_f32 v[72:73], v[72:73], v[82:83]
	v_pk_mul_f32 v[62:63], v[62:63], v[134:135] op_sel_hi:[1,0]
	v_cvt_pk_bf16_f32 v64, v72, v73
	v_cvt_pk_bf16_f32 v65, v74, v75
	v_cvt_pk_bf16_f32 v66, v66, v67
	v_cvt_pk_bf16_f32 v67, v68, v69
	v_mad_i64_i32 v[68:69], s[4:5], v174, s35, v[112:113]
	v_lshl_add_u64 v[68:69], v[68:69], 0, v[114:115]
	v_pk_mul_f32 v[60:61], v[60:61], v[134:135] op_sel_hi:[1,0]
	v_pk_mul_f32 v[58:59], v[58:59], v[134:135] op_sel_hi:[1,0]
	v_pk_mul_f32 v[56:57], v[56:57], v[134:135] op_sel_hi:[1,0]
	v_pk_mul_f32 v[54:55], v[54:55], v[134:135] op_sel_hi:[1,0]
	v_pk_mul_f32 v[52:53], v[52:53], v[134:135] op_sel_hi:[1,0]
	global_store_dwordx4 v[68:69], v[64:67], off
	v_pk_mul_f32 v[56:57], v[60:61], v[56:57]
	v_pk_mul_f32 v[58:59], v[62:63], v[58:59]
	v_pk_mul_f32 v[64:65], v[62:63], s[44:45] op_sel_hi:[1,0]
	v_pk_mul_f32 v[66:67], v[60:61], s[44:45] op_sel_hi:[1,0]
	v_pk_mul_f32 v[60:61], v[54:55], s[44:45] op_sel_hi:[1,0]
	v_pk_mul_f32 v[62:63], v[52:53], s[44:45] op_sel_hi:[1,0]
	v_exp_f32_e32 v60, v60
	v_exp_f32_e32 v62, v62
	v_exp_f32_e32 v61, v61
	v_exp_f32_e32 v63, v63
	v_exp_f32_e32 v66, v66
	v_exp_f32_e32 v64, v64
	v_exp_f32_e32 v65, v65
	v_exp_f32_e32 v67, v67
	v_pk_add_f32 v[60:61], v[60:61], 1.0 op_sel_hi:[1,0]
	v_pk_add_f32 v[62:63], v[62:63], 1.0 op_sel_hi:[1,0]
	v_pk_add_f32 v[64:65], v[64:65], 1.0 op_sel_hi:[1,0]
	v_pk_add_f32 v[66:67], v[66:67], 1.0 op_sel_hi:[1,0]
	v_rcp_f32_e32 v62, v62
	v_rcp_f32_e32 v60, v60
	v_rcp_f32_e32 v61, v61
	v_rcp_f32_e32 v63, v63
	v_rcp_f32_e32 v66, v66
	v_rcp_f32_e32 v64, v64
	v_rcp_f32_e32 v65, v65
	v_rcp_f32_e32 v67, v67
	v_pk_mul_f32 v[50:51], v[50:51], v[134:135] op_sel_hi:[1,0]
	v_pk_mul_f32 v[48:49], v[48:49], v[134:135] op_sel_hi:[1,0]
	v_pk_mul_f32 v[50:51], v[54:55], v[50:51]
	v_pk_mul_f32 v[48:49], v[52:53], v[48:49]
	v_mul_f32_e32 v132, 0x45800000, v135
	v_pk_mul_f32 v[52:53], v[50:51], v[60:61]
	v_pk_mul_f32 v[50:51], v[48:49], v[62:63]
	v_cndmask_b32_e64 v132, v135, v132, s[6:7]
	v_pk_mul_f32 v[58:59], v[58:59], v[64:65]
	v_pk_mul_f32 v[56:57], v[56:57], v[66:67]
	v_pk_mul_f32 v[46:47], v[46:47], v[132:133] op_sel_hi:[1,0]
	v_cvt_pk_bf16_f32 v48, v56, v57
	v_cvt_pk_bf16_f32 v49, v58, v59
	v_cvt_pk_bf16_f32 v50, v50, v51
	v_cvt_pk_bf16_f32 v51, v52, v53
	v_mad_i64_i32 v[52:53], s[4:5], v172, s35, v[112:113]
	v_lshl_add_u64 v[52:53], v[52:53], 0, v[114:115]
	v_pk_mul_f32 v[44:45], v[44:45], v[132:133] op_sel_hi:[1,0]
	v_pk_mul_f32 v[42:43], v[42:43], v[132:133] op_sel_hi:[1,0]
	v_pk_mul_f32 v[40:41], v[40:41], v[132:133] op_sel_hi:[1,0]
	v_pk_mul_f32 v[38:39], v[38:39], v[132:133] op_sel_hi:[1,0]
	v_pk_mul_f32 v[36:37], v[36:37], v[132:133] op_sel_hi:[1,0]
	global_store_dwordx4 v[52:53], v[48:51], off
	v_pk_mul_f32 v[40:41], v[44:45], v[40:41]
	v_pk_mul_f32 v[42:43], v[46:47], v[42:43]
	v_pk_mul_f32 v[48:49], v[46:47], s[44:45] op_sel_hi:[1,0]
	v_pk_mul_f32 v[50:51], v[44:45], s[44:45] op_sel_hi:[1,0]
	v_pk_mul_f32 v[44:45], v[38:39], s[44:45] op_sel_hi:[1,0]
	v_pk_mul_f32 v[46:47], v[36:37], s[44:45] op_sel_hi:[1,0]
	v_exp_f32_e32 v44, v44
	v_exp_f32_e32 v46, v46
	v_exp_f32_e32 v45, v45
	v_exp_f32_e32 v47, v47
	v_exp_f32_e32 v50, v50
	v_exp_f32_e32 v48, v48
	v_exp_f32_e32 v49, v49
	v_exp_f32_e32 v51, v51
	v_pk_add_f32 v[44:45], v[44:45], 1.0 op_sel_hi:[1,0]
	v_pk_add_f32 v[46:47], v[46:47], 1.0 op_sel_hi:[1,0]
	v_pk_add_f32 v[48:49], v[48:49], 1.0 op_sel_hi:[1,0]
	v_pk_add_f32 v[50:51], v[50:51], 1.0 op_sel_hi:[1,0]
	v_rcp_f32_e32 v46, v46
	v_rcp_f32_e32 v44, v44
	v_rcp_f32_e32 v45, v45
	v_rcp_f32_e32 v47, v47
	v_rcp_f32_e32 v50, v50
	v_rcp_f32_e32 v48, v48
	v_rcp_f32_e32 v49, v49
	v_rcp_f32_e32 v51, v51
	v_pk_mul_f32 v[34:35], v[34:35], v[132:133] op_sel_hi:[1,0]
	v_pk_mul_f32 v[32:33], v[32:33], v[132:133] op_sel_hi:[1,0]
	v_pk_mul_f32 v[34:35], v[38:39], v[34:35]
	v_pk_mul_f32 v[32:33], v[36:37], v[32:33]
	v_pk_mul_f32 v[36:37], v[34:35], v[44:45]
	v_pk_mul_f32 v[34:35], v[32:33], v[46:47]
	v_pk_mul_f32 v[42:43], v[42:43], v[48:49]
	v_pk_mul_f32 v[40:41], v[40:41], v[50:51]
	v_pk_mul_f32 v[30:31], v[30:31], v[130:131] op_sel_hi:[1,0]
	v_cvt_pk_bf16_f32 v32, v40, v41
	v_cvt_pk_bf16_f32 v33, v42, v43
	v_cvt_pk_bf16_f32 v34, v34, v35
	v_cvt_pk_bf16_f32 v35, v36, v37
	v_mad_i64_i32 v[36:37], s[4:5], v170, s35, v[112:113]
	v_lshl_add_u64 v[36:37], v[36:37], 0, v[114:115]
	v_pk_mul_f32 v[28:29], v[28:29], v[130:131] op_sel_hi:[1,0]
	v_pk_mul_f32 v[26:27], v[26:27], v[130:131] op_sel_hi:[1,0]
	v_pk_mul_f32 v[24:25], v[24:25], v[130:131] op_sel_hi:[1,0]
	v_pk_mul_f32 v[22:23], v[22:23], v[130:131] op_sel_hi:[1,0]
	v_pk_mul_f32 v[20:21], v[20:21], v[130:131] op_sel_hi:[1,0]
	global_store_dwordx4 v[36:37], v[32:35], off
	v_pk_mul_f32 v[24:25], v[28:29], v[24:25]
	v_pk_mul_f32 v[26:27], v[30:31], v[26:27]
	v_pk_mul_f32 v[32:33], v[30:31], s[44:45] op_sel_hi:[1,0]
	v_pk_mul_f32 v[34:35], v[28:29], s[44:45] op_sel_hi:[1,0]
	v_pk_mul_f32 v[28:29], v[22:23], s[44:45] op_sel_hi:[1,0]
	v_pk_mul_f32 v[30:31], v[20:21], s[44:45] op_sel_hi:[1,0]
	v_exp_f32_e32 v28, v28
	v_exp_f32_e32 v30, v30
	v_exp_f32_e32 v29, v29
	v_exp_f32_e32 v31, v31
	v_exp_f32_e32 v34, v34
	v_exp_f32_e32 v32, v32
	v_exp_f32_e32 v33, v33
	v_exp_f32_e32 v35, v35
	v_pk_add_f32 v[28:29], v[28:29], 1.0 op_sel_hi:[1,0]
	v_pk_add_f32 v[30:31], v[30:31], 1.0 op_sel_hi:[1,0]
	v_pk_add_f32 v[32:33], v[32:33], 1.0 op_sel_hi:[1,0]
	v_pk_add_f32 v[34:35], v[34:35], 1.0 op_sel_hi:[1,0]
	v_rcp_f32_e32 v30, v30
	v_rcp_f32_e32 v28, v28
	v_rcp_f32_e32 v29, v29
	v_rcp_f32_e32 v31, v31
	v_rcp_f32_e32 v34, v34
	v_rcp_f32_e32 v32, v32
	v_rcp_f32_e32 v33, v33
	v_rcp_f32_e32 v35, v35
	v_pk_mul_f32 v[18:19], v[18:19], v[130:131] op_sel_hi:[1,0]
	v_pk_mul_f32 v[16:17], v[16:17], v[130:131] op_sel_hi:[1,0]
	v_pk_mul_f32 v[18:19], v[22:23], v[18:19]
	v_pk_mul_f32 v[16:17], v[20:21], v[16:17]
	v_pk_mul_f32 v[20:21], v[18:19], v[28:29]
	v_pk_mul_f32 v[18:19], v[16:17], v[30:31]
	v_pk_mul_f32 v[26:27], v[26:27], v[32:33]
	v_pk_mul_f32 v[24:25], v[24:25], v[34:35]
	v_pk_mul_f32 v[14:15], v[14:15], v[128:129] op_sel_hi:[1,0]
	v_cvt_pk_bf16_f32 v16, v24, v25
	v_cvt_pk_bf16_f32 v17, v26, v27
	v_cvt_pk_bf16_f32 v18, v18, v19
	v_cvt_pk_bf16_f32 v19, v20, v21
	v_mad_i64_i32 v[20:21], s[4:5], v168, s35, v[112:113]
	v_lshl_add_u64 v[20:21], v[20:21], 0, v[114:115]
	v_pk_mul_f32 v[12:13], v[12:13], v[128:129] op_sel_hi:[1,0]
	v_pk_mul_f32 v[10:11], v[10:11], v[128:129] op_sel_hi:[1,0]
	v_pk_mul_f32 v[8:9], v[8:9], v[128:129] op_sel_hi:[1,0]
	v_pk_mul_f32 v[6:7], v[6:7], v[128:129] op_sel_hi:[1,0]
	v_pk_mul_f32 v[4:5], v[4:5], v[128:129] op_sel_hi:[1,0]
	global_store_dwordx4 v[20:21], v[16:19], off
	v_pk_mul_f32 v[8:9], v[12:13], v[8:9]
	v_pk_mul_f32 v[10:11], v[14:15], v[10:11]
	v_pk_mul_f32 v[16:17], v[14:15], s[44:45] op_sel_hi:[1,0]
	v_pk_mul_f32 v[18:19], v[12:13], s[44:45] op_sel_hi:[1,0]
	v_pk_mul_f32 v[12:13], v[6:7], s[44:45] op_sel_hi:[1,0]
	v_pk_mul_f32 v[14:15], v[4:5], s[44:45] op_sel_hi:[1,0]
	v_exp_f32_e32 v12, v12
	v_exp_f32_e32 v14, v14
	v_exp_f32_e32 v13, v13
	v_exp_f32_e32 v15, v15
	v_exp_f32_e32 v18, v18
	v_exp_f32_e32 v16, v16
	v_exp_f32_e32 v17, v17
	v_exp_f32_e32 v19, v19
	v_pk_add_f32 v[12:13], v[12:13], 1.0 op_sel_hi:[1,0]
	v_pk_add_f32 v[14:15], v[14:15], 1.0 op_sel_hi:[1,0]
	v_pk_add_f32 v[16:17], v[16:17], 1.0 op_sel_hi:[1,0]
	v_pk_add_f32 v[18:19], v[18:19], 1.0 op_sel_hi:[1,0]
	v_rcp_f32_e32 v14, v14
	v_rcp_f32_e32 v12, v12
	v_rcp_f32_e32 v13, v13
	v_rcp_f32_e32 v15, v15
	v_rcp_f32_e32 v18, v18
	v_rcp_f32_e32 v16, v16
	v_rcp_f32_e32 v17, v17
	v_rcp_f32_e32 v19, v19
	v_pk_mul_f32 v[2:3], v[2:3], v[128:129] op_sel_hi:[1,0]
	v_pk_mul_f32 v[0:1], v[0:1], v[128:129] op_sel_hi:[1,0]
	v_pk_mul_f32 v[2:3], v[6:7], v[2:3]
	v_pk_mul_f32 v[0:1], v[4:5], v[0:1]
	v_pk_mul_f32 v[4:5], v[2:3], v[12:13]
	v_pk_mul_f32 v[2:3], v[0:1], v[14:15]
	v_pk_mul_f32 v[10:11], v[10:11], v[16:17]
	v_pk_mul_f32 v[8:9], v[8:9], v[18:19]
	s_andn2_b64 vcc, exec, s[2:3]
	v_cvt_pk_bf16_f32 v0, v8, v9
	v_cvt_pk_bf16_f32 v1, v10, v11
	v_cvt_pk_bf16_f32 v2, v2, v3
	v_cvt_pk_bf16_f32 v3, v4, v5
	v_mad_i64_i32 v[4:5], s[4:5], v166, s35, v[112:113]
	v_lshl_add_u64 v[4:5], v[4:5], 0, v[114:115]
	s_mov_b32 s4, s16
	s_mov_b32 s5, s12
	s_mov_b64 s[6:7], s[18:19]
	global_store_dwordx4 v[4:5], v[0:3], off
	s_cbranch_vccnz .LBB0_1429
	s_waitcnt vmcnt(0)
	s_cmpk_gt_u32 s24, 0xff
	s_cbranch_scc1 .LBB0_1440
	s_barrier
